# pipelined epilogue loads P7/P8/P12 (batched, counted vmcnt), P7 mid-hook loads batched, removed cg grid.sync
# speedup vs baseline: 1.0278x; 1.0278x over previous
; #define LAS __attribute__((address_space(3)))
; __global__ void __launch_bounds__(NTHR, 2) fwd_megakernel(Args A) {
;     ...
;     cg::grid_group grid = cg::this_grid();
;     LAS unsigned char* lds = (LAS unsigned char*)lds_raw;
;     const int G = gridDim.x, blk = blockIdx.x, NGW = G * NWAVES;
;     { volatile LAS unsigned* mz = (volatile LAS unsigned*)(lds + MISC_OFF); if (threadIdx.x < 64) mz[threadIdx.x] = 0u; }
;     __syncthreads();
;     grid.sync();
;     const XcdBarrier bar = xcd_barrier_post((unsigned*)(A.ws + WS_CTL), (volatile LAS unsigned*)(lds + MISC_OFF) + 8);
.LBB0_12:
	s_load_dwordx16 s[52:67], s[0:1], 0x0
	s_load_dwordx16 s[68:83], s[0:1], 0x40
	s_load_dwordx16 s[4:19], s[0:1], 0x80
	s_add_u32 s0, s26, 0x780000
	s_addc_u32 s1, s27, 0
	s_barrier
	s_waitcnt lgkmcnt(0)
	v_writelane_b32 v242, s4, 1
	v_cmp_eq_u32_e64 s[42:43], 0, v189
	s_nop 0
	v_writelane_b32 v242, s5, 2
	v_writelane_b32 v242, s6, 3
	v_writelane_b32 v242, s7, 4
	v_writelane_b32 v242, s8, 5
	v_writelane_b32 v242, s9, 6
	v_writelane_b32 v242, s10, 7
	v_writelane_b32 v242, s11, 8
	v_writelane_b32 v242, s12, 9
	v_writelane_b32 v242, s13, 10
	v_writelane_b32 v242, s14, 11
	v_writelane_b32 v242, s15, 12
	v_writelane_b32 v242, s16, 13
	v_writelane_b32 v242, s17, 14
	v_writelane_b32 v242, s18, 15
	v_writelane_b32 v242, s19, 16
	v_writelane_b32 v242, s0, 17
	s_nop 1
	v_writelane_b32 v242, s1, 18
	s_getreg_b32 s0, hwreg(HW_REG_XCC_ID, 0, 4)
	s_and_b32 s0, s0, 15
	v_writelane_b32 v242, s0, 19
	s_and_saveexec_b64 s[0:1], s[42:43]
	s_cbranch_execz .LBB0_15
	s_mov_b64 s[2:3], exec
	v_mbcnt_lo_u32_b32 v0, s2, 0
	v_mbcnt_hi_u32_b32 v0, s3, v0
	v_cmp_eq_u32_e32 vcc, 0, v0
	s_and_b64 s[4:5], exec, vcc
	s_mov_b64 exec, s[4:5]
	s_cbranch_execz .LBB0_15
	v_readlane_b32 s4, v242, 19
	s_bcnt1_i32_b64 s2, s[2:3]
	s_lshl_b32 s4, s4, 8
	v_mov_b32_e32 v1, s2
	v_readlane_b32 s2, v242, 17
	v_mov_b32_e32 v0, s4
	v_readlane_b32 s3, v242, 18
	s_nop 4
	global_atomic_add v0, v1, s[2:3] offset:1024

; #define PG8_STAGE(bufoff, gbase, voff) do { _Pragma("unroll") for (int _i = 0; _i < 2; ++_i) \
;         __builtin_amdgcn_global_load_lds((const unsigned*)((const char*)(gbase) + (voff)[_i]), (PG8_LAS unsigned*)(lds + (bufoff) + ldsw + _i * 8192), 16, 0, 0); } while (0)
; #define PG8_LDA(dst, b, h) do { _Pragma("unroll") for (int m = 0; m < 4; ++m) _Pragma("unroll") for (int k = 0; k < 2; ++k) dst[m][k] = *(const PG8_LAS bf16x8*)(lds + PG8_SA(b, h) + aoff + m * 2048 + k * 1024); } while (0)
; #define PG8_LDB(dst, b, h) do { _Pragma("unroll") for (int n = 0; n < 2; ++n) _Pragma("unroll") for (int k = 0; k < 2; ++k) dst[n][k] = *(const PG8_LAS bf16x8*)(lds + PG8_SB(b, h) + boff + n * 2048 + k * 1024); } while (0)
; #define PG8_MMA(ai, bj, At, Bt) do { __builtin_amdgcn_s_setprio(1); _Pragma("unroll") for (int m = 0; m < 4; ++m) _Pragma("unroll") for (int n = 0; n < 2; ++n) _Pragma("unroll") for (int k = 0; k < 2; ++k) \
;         acc[ai][bj][m][n] = __builtin_amdgcn_mfma_f32_16x16x32_bf16(Bt[n][k], At[m][k], acc[ai][bj][m][n], 0, 0, 0); __builtin_amdgcn_s_setprio(0); } while (0)
; #define PG8_WAIT_V(n) asm volatile("s_waitcnt vmcnt(" #n ")" ::: "memory")
; #define PG8_WAIT_L(n) asm volatile("s_waitcnt lgkmcnt(" #n ")" ::: "memory")
; #define PG8_BAR __builtin_amdgcn_s_barrier()
; #define PG8_SCHED __builtin_amdgcn_sched_barrier(0)
; template <class Epi, class Sched, bool ALIGN_EPI = false, bool SP2 = false>
; __device__ __forceinline__ void gemm_phase(PG8_LAS unsigned char* lds, const Gemm g, const Sched& S, const Epi& E) {
;     ...
;             PG8_LDB(B0, 0, 0); PG8_LDB(B1, 0, 1); PG8_SCHED; PG8_LDA(At, 0, 0); PG8_STAGE(PG8_SA(1, 1), a1 + hstep, voffA);
;             PG8_WAIT_V(8); PG8_WAIT_L(0); PG8_BAR; PG8_MMA(0, 0, At, B0); PG8_MMA(0, 1, At, B1); PG8_BAR; PG8_SCHED;
;             PG8_LDA(At, 0, 1); PG8_STAGE(PG8_SB(0, 0), b2, voffB); PG8_STAGE(PG8_SB(0, 1), b2 + hstep, voffB); PG8_STAGE(PG8_SA(0, 0), a2, voffA);
;             PG8_WAIT_V(8); PG8_WAIT_L(0); PG8_BAR; PG8_MMA(1, 0, At, B0); PG8_MMA(1, 1, At, B1); PG8_BAR; PG8_SCHED;
.LBB0_703:
	ds_read_b128 v[162:165], v159
	ds_read_b128 v[166:169], v159 offset:1024
	ds_read_b128 v[170:173], v159 offset:2048
	ds_read_b128 v[174:177], v159 offset:3072
	ds_read_b128 v[178:181], v160
	ds_read_b128 v[182:185], v160 offset:1024
	ds_read_b128 v[190:193], v160 offset:2048
	ds_read_b128 v[194:197], v160 offset:3072
	v_lshl_add_u64 v[210:211], v[148:149], 0, s[64:65]
	s_mov_b32 m0, s77
	v_lshl_add_u64 v[186:187], v[210:211], 0, s[10:11]
	v_lshl_add_u64 v[234:235], v[150:151], 0, s[64:65]
	ds_read_b128 v[198:201], v161
	ds_read_b128 v[202:205], v161 offset:1024
	ds_read_b128 v[206:209], v161 offset:2048
	ds_read_b128 v[214:217], v161 offset:3072
	ds_read_b128 v[218:221], v161 offset:4096
	ds_read_b128 v[222:225], v161 offset:5120
	ds_read_b128 v[226:229], v161 offset:6144
	ds_read_b128 v[230:233], v161 offset:7168
	global_load_lds_dwordx4 v[186:187], off
	v_lshl_add_u64 v[186:187], v[234:235], 0, s[10:11]
	s_mov_b32 m0, s78
	s_nop 0
	global_load_lds_dwordx4 v[186:187], off
	s_waitcnt vmcnt(8)
	s_waitcnt lgkmcnt(0)
	s_barrier
	s_setprio 1
	s_waitcnt lgkmcnt(0)
	v_mfma_f32_16x16x32_bf16 v[124:127], v[162:165], v[198:201], v[124:127]
	v_mfma_f32_16x16x32_bf16 v[120:123], v[170:173], v[198:201], v[120:123]
	v_mfma_f32_16x16x32_bf16 v[116:119], v[162:165], v[206:209], v[116:119]
	v_mfma_f32_16x16x32_bf16 v[112:115], v[170:173], v[206:209], v[112:115]
	v_mfma_f32_16x16x32_bf16 v[108:111], v[162:165], v[218:221], v[108:111]
	v_mfma_f32_16x16x32_bf16 v[104:107], v[170:173], v[218:221], v[104:107]
	v_mfma_f32_16x16x32_bf16 v[100:103], v[162:165], v[226:229], v[100:103]
	v_mfma_f32_16x16x32_bf16 v[96:99], v[170:173], v[226:229], v[96:99]
	v_mfma_f32_16x16x32_bf16 v[124:127], v[166:169], v[202:205], v[124:127]
	v_mfma_f32_16x16x32_bf16 v[120:123], v[174:177], v[202:205], v[120:123]
	v_mfma_f32_16x16x32_bf16 v[116:119], v[166:169], v[214:217], v[116:119]
	v_mfma_f32_16x16x32_bf16 v[112:115], v[174:177], v[214:217], v[112:115]
	v_mfma_f32_16x16x32_bf16 v[108:111], v[166:169], v[222:225], v[108:111]
	v_mfma_f32_16x16x32_bf16 v[104:107], v[174:177], v[222:225], v[104:107]
	v_mfma_f32_16x16x32_bf16 v[100:103], v[166:169], v[230:233], v[100:103]
	v_mfma_f32_16x16x32_bf16 v[96:99], v[174:177], v[230:233], v[96:99]
	s_setprio 0
	s_setprio 1
	v_mfma_f32_16x16x32_bf16 v[88:91], v[178:181], v[198:201], v[88:91]
	v_mfma_f32_16x16x32_bf16 v[92:95], v[190:193], v[198:201], v[92:95]
	v_mfma_f32_16x16x32_bf16 v[80:83], v[178:181], v[206:209], v[80:83]
	v_mfma_f32_16x16x32_bf16 v[84:87], v[190:193], v[206:209], v[84:87]
	v_mfma_f32_16x16x32_bf16 v[72:75], v[178:181], v[218:221], v[72:75]
	v_mfma_f32_16x16x32_bf16 v[76:79], v[190:193], v[218:221], v[76:79]
	v_mfma_f32_16x16x32_bf16 v[64:67], v[178:181], v[226:229], v[64:67]
	v_mfma_f32_16x16x32_bf16 v[68:71], v[190:193], v[226:229], v[68:71]
	v_mfma_f32_16x16x32_bf16 v[88:91], v[182:185], v[202:205], v[88:91]
	v_mfma_f32_16x16x32_bf16 v[92:95], v[194:197], v[202:205], v[92:95]
	v_mfma_f32_16x16x32_bf16 v[80:83], v[182:185], v[214:217], v[80:83]
	v_mfma_f32_16x16x32_bf16 v[84:87], v[194:197], v[214:217], v[84:87]
	v_mfma_f32_16x16x32_bf16 v[72:75], v[182:185], v[222:225], v[72:75]
	v_mfma_f32_16x16x32_bf16 v[76:79], v[194:197], v[222:225], v[76:79]
	v_mfma_f32_16x16x32_bf16 v[64:67], v[182:185], v[230:233], v[64:67]
	v_mfma_f32_16x16x32_bf16 v[68:71], v[194:197], v[230:233], v[68:71]
	s_setprio 0
	s_barrier
	v_lshl_add_u64 v[236:237], v[152:153], 0, s[64:65]
	s_mov_b32 m0, s79
	v_lshl_add_u64 v[186:187], v[236:237], 0, s[14:15]
	v_lshl_add_u64 v[238:239], v[154:155], 0, s[64:65]
	ds_read_b128 v[198:201], v161 offset:16384
	ds_read_b128 v[202:205], v161 offset:17408
	ds_read_b128 v[206:209], v161 offset:18432
	ds_read_b128 v[214:217], v161 offset:19456
	ds_read_b128 v[218:221], v161 offset:20480
	ds_read_b128 v[222:225], v161 offset:21504
	ds_read_b128 v[226:229], v161 offset:22528
	ds_read_b128 v[230:233], v161 offset:23552
	global_load_lds_dwordx4 v[186:187], off
	v_lshl_add_u64 v[186:187], v[238:239], 0, s[14:15]
	s_mov_b32 m0, s80
	s_add_i32 s0, s74, s23
	global_load_lds_dwordx4 v[186:187], off
	v_lshl_add_u64 v[186:187], v[236:237], 0, s[36:37]
	s_mov_b32 m0, s0
	s_add_i32 s1, s0, 0x2000
	global_load_lds_dwordx4 v[186:187], off
	v_lshl_add_u64 v[186:187], v[238:239], 0, s[36:37]
	s_mov_b32 m0, s1
	s_nop 0
	global_load_lds_dwordx4 v[186:187], off
	v_lshl_add_u64 v[186:187], v[210:211], 0, s[14:15]
	s_mov_b32 m0, s28
	s_nop 0
	global_load_lds_dwordx4 v[186:187], off
	v_lshl_add_u64 v[186:187], v[234:235], 0, s[14:15]
	s_mov_b32 m0, s29
	s_nop 0
	global_load_lds_dwordx4 v[186:187], off
	s_waitcnt vmcnt(8)
	s_waitcnt lgkmcnt(0)
	s_barrier
; #define PG8_STAGE(bufoff, gbase, voff) do { _Pragma("unroll") for (int _i = 0; _i < 2; ++_i) \
;         __builtin_amdgcn_global_load_lds((const unsigned*)((const char*)(gbase) + (voff)[_i]), (PG8_LAS unsigned*)(lds + (bufoff) + ldsw + _i * 8192), 16, 0, 0); } while (0)
; #define PG8_LDA(dst, b, h) do { _Pragma("unroll") for (int m = 0; m < 4; ++m) _Pragma("unroll") for (int k = 0; k < 2; ++k) dst[m][k] = *(const PG8_LAS bf16x8*)(lds + PG8_SA(b, h) + aoff + m * 2048 + k * 1024); } while (0)
; #define PG8_LDB(dst, b, h) do { _Pragma("unroll") for (int n = 0; n < 2; ++n) _Pragma("unroll") for (int k = 0; k < 2; ++k) dst[n][k] = *(const PG8_LAS bf16x8*)(lds + PG8_SB(b, h) + boff + n * 2048 + k * 1024); } while (0)
; #define PG8_MMA(ai, bj, At, Bt) do { __builtin_amdgcn_s_setprio(1); _Pragma("unroll") for (int m = 0; m < 4; ++m) _Pragma("unroll") for (int n = 0; n < 2; ++n) _Pragma("unroll") for (int k = 0; k < 2; ++k) \
;         acc[ai][bj][m][n] = __builtin_amdgcn_mfma_f32_16x16x32_bf16(Bt[n][k], At[m][k], acc[ai][bj][m][n], 0, 0, 0); __builtin_amdgcn_s_setprio(0); } while (0)
; #define PG8_WAIT_V(n) asm volatile("s_waitcnt vmcnt(" #n ")" ::: "memory")
; #define PG8_WAIT_L(n) asm volatile("s_waitcnt lgkmcnt(" #n ")" ::: "memory")
; #define PG8_BAR __builtin_amdgcn_s_barrier()
; #define PG8_SCHED __builtin_amdgcn_sched_barrier(0)
; template <class Epi, class Sched, bool ALIGN_EPI = false, bool SP2 = false>
; __device__ __forceinline__ void gemm_phase(PG8_LAS unsigned char* lds, const Gemm g, const Sched& S, const Epi& E) {
;     ...
;             PG8_WAIT_V(8); PG8_WAIT_L(0); PG8_BAR; PG8_MMA(1, 0, At, B0); PG8_MMA(1, 1, At, B1); PG8_BAR; PG8_SCHED;
;             PG8_LDB(B0, 1, 0); PG8_LDB(B1, 1, 1); PG8_SCHED; PG8_LDA(At, 1, 0); PG8_STAGE(PG8_SA(0, 1), a2 + hstep, voffA);
;             PG8_WAIT_V(8); PG8_WAIT_L(0); PG8_BAR; PG8_MMA(0, 0, At, B0); PG8_MMA(0, 1, At, B1); PG8_BAR; PG8_SCHED;
;             PG8_LDA(At, 1, 1); PG8_STAGE(PG8_SB(1, 0), b3, voffB); PG8_STAGE(PG8_SB(1, 1), b3 + hstep, voffB); PG8_STAGE(PG8_SA(1, 0), a3, voffA);
	s_setprio 1
	s_waitcnt lgkmcnt(0)
	v_mfma_f32_16x16x32_bf16 v[60:63], v[162:165], v[198:201], v[60:63]
	v_mfma_f32_16x16x32_bf16 v[56:59], v[170:173], v[198:201], v[56:59]
	v_mfma_f32_16x16x32_bf16 v[44:47], v[162:165], v[206:209], v[44:47]
	v_mfma_f32_16x16x32_bf16 v[40:43], v[170:173], v[206:209], v[40:43]
	v_mfma_f32_16x16x32_bf16 v[28:31], v[162:165], v[218:221], v[28:31]
	v_mfma_f32_16x16x32_bf16 v[24:27], v[170:173], v[218:221], v[24:27]
	v_mfma_f32_16x16x32_bf16 v[12:15], v[162:165], v[226:229], v[12:15]
	v_mfma_f32_16x16x32_bf16 v[8:11], v[170:173], v[226:229], v[8:11]
	v_mfma_f32_16x16x32_bf16 v[60:63], v[166:169], v[202:205], v[60:63]
	v_mfma_f32_16x16x32_bf16 v[56:59], v[174:177], v[202:205], v[56:59]
	v_mfma_f32_16x16x32_bf16 v[44:47], v[166:169], v[214:217], v[44:47]
	v_mfma_f32_16x16x32_bf16 v[40:43], v[174:177], v[214:217], v[40:43]
	v_mfma_f32_16x16x32_bf16 v[28:31], v[166:169], v[222:225], v[28:31]
	v_mfma_f32_16x16x32_bf16 v[24:27], v[174:177], v[222:225], v[24:27]
	v_mfma_f32_16x16x32_bf16 v[12:15], v[166:169], v[230:233], v[12:15]
	v_mfma_f32_16x16x32_bf16 v[8:11], v[174:177], v[230:233], v[8:11]
	s_setprio 0
	s_setprio 1
	v_mfma_f32_16x16x32_bf16 v[52:55], v[178:181], v[198:201], v[52:55]
	v_mfma_f32_16x16x32_bf16 v[48:51], v[190:193], v[198:201], v[48:51]
	v_mfma_f32_16x16x32_bf16 v[36:39], v[178:181], v[206:209], v[36:39]
	v_mfma_f32_16x16x32_bf16 v[32:35], v[190:193], v[206:209], v[32:35]
	v_mfma_f32_16x16x32_bf16 v[20:23], v[178:181], v[218:221], v[20:23]
	v_mfma_f32_16x16x32_bf16 v[16:19], v[190:193], v[218:221], v[16:19]
	v_mfma_f32_16x16x32_bf16 v[4:7], v[178:181], v[226:229], v[4:7]
	v_mfma_f32_16x16x32_bf16 v[0:3], v[190:193], v[226:229], v[0:3]
	v_mfma_f32_16x16x32_bf16 v[52:55], v[182:185], v[202:205], v[52:55]
	v_mfma_f32_16x16x32_bf16 v[48:51], v[194:197], v[202:205], v[48:51]
	v_mfma_f32_16x16x32_bf16 v[36:39], v[182:185], v[214:217], v[36:39]
	v_mfma_f32_16x16x32_bf16 v[32:35], v[194:197], v[214:217], v[32:35]
	v_mfma_f32_16x16x32_bf16 v[20:23], v[182:185], v[222:225], v[20:23]
	v_mfma_f32_16x16x32_bf16 v[16:19], v[194:197], v[222:225], v[16:19]
	v_mfma_f32_16x16x32_bf16 v[4:7], v[182:185], v[230:233], v[4:7]
	v_mfma_f32_16x16x32_bf16 v[0:3], v[194:197], v[230:233], v[0:3]
	s_setprio 0
	s_barrier
	v_add_u32_e32 v162, s75, v157
	v_add_u32_e32 v163, s84, v157
	ds_read_b128 v[164:167], v162
	ds_read_b128 v[168:171], v162 offset:1024
	ds_read_b128 v[172:175], v162 offset:2048
	ds_read_b128 v[176:179], v162 offset:3072
	ds_read_b128 v[180:183], v163
	ds_read_b128 v[184:187], v163 offset:1024
	ds_read_b128 v[190:193], v163 offset:2048
	ds_read_b128 v[194:197], v163 offset:3072
	s_mov_b32 m0, s30
	v_lshl_add_u64 v[240:241], v[210:211], 0, s[36:37]
	ds_read_b128 v[198:201], v161 offset:32768
	ds_read_b128 v[202:205], v161 offset:33792
	ds_read_b128 v[206:209], v161 offset:34816
	ds_read_b128 v[214:217], v161 offset:35840
	ds_read_b128 v[218:221], v161 offset:36864
	ds_read_b128 v[222:225], v161 offset:37888
	ds_read_b128 v[226:229], v161 offset:38912
	ds_read_b128 v[230:233], v161 offset:39936
	global_load_lds_dwordx4 v[240:241], off
	v_lshl_add_u64 v[240:241], v[234:235], 0, s[36:37]
	s_mov_b32 m0, s33
	s_nop 0
	global_load_lds_dwordx4 v[240:241], off
	s_waitcnt vmcnt(8)
	s_waitcnt lgkmcnt(0)
	s_barrier
	s_setprio 1
	s_waitcnt lgkmcnt(0)
	v_mfma_f32_16x16x32_bf16 v[124:127], v[164:167], v[198:201], v[124:127]
	v_mfma_f32_16x16x32_bf16 v[120:123], v[172:175], v[198:201], v[120:123]
	v_mfma_f32_16x16x32_bf16 v[116:119], v[164:167], v[206:209], v[116:119]
	v_mfma_f32_16x16x32_bf16 v[112:115], v[172:175], v[206:209], v[112:115]
	v_mfma_f32_16x16x32_bf16 v[108:111], v[164:167], v[218:221], v[108:111]
	v_mfma_f32_16x16x32_bf16 v[104:107], v[172:175], v[218:221], v[104:107]
	v_mfma_f32_16x16x32_bf16 v[100:103], v[164:167], v[226:229], v[100:103]
	v_mfma_f32_16x16x32_bf16 v[96:99], v[172:175], v[226:229], v[96:99]
	v_mfma_f32_16x16x32_bf16 v[124:127], v[168:171], v[202:205], v[124:127]
	v_mfma_f32_16x16x32_bf16 v[120:123], v[176:179], v[202:205], v[120:123]
	v_mfma_f32_16x16x32_bf16 v[116:119], v[168:171], v[214:217], v[116:119]
	v_mfma_f32_16x16x32_bf16 v[112:115], v[176:179], v[214:217], v[112:115]
	v_mfma_f32_16x16x32_bf16 v[108:111], v[168:171], v[222:225], v[108:111]
	v_mfma_f32_16x16x32_bf16 v[104:107], v[176:179], v[222:225], v[104:107]
	v_mfma_f32_16x16x32_bf16 v[100:103], v[168:171], v[230:233], v[100:103]
	v_mfma_f32_16x16x32_bf16 v[96:99], v[176:179], v[230:233], v[96:99]
	s_setprio 0
	s_setprio 1
	v_mfma_f32_16x16x32_bf16 v[88:91], v[180:183], v[198:201], v[88:91]
	v_mfma_f32_16x16x32_bf16 v[92:95], v[190:193], v[198:201], v[92:95]
	v_mfma_f32_16x16x32_bf16 v[80:83], v[180:183], v[206:209], v[80:83]
	v_mfma_f32_16x16x32_bf16 v[84:87], v[190:193], v[206:209], v[84:87]
	v_mfma_f32_16x16x32_bf16 v[72:75], v[180:183], v[218:221], v[72:75]
	v_mfma_f32_16x16x32_bf16 v[76:79], v[190:193], v[218:221], v[76:79]
	v_mfma_f32_16x16x32_bf16 v[64:67], v[180:183], v[226:229], v[64:67]
	v_mfma_f32_16x16x32_bf16 v[68:71], v[190:193], v[226:229], v[68:71]
	v_mfma_f32_16x16x32_bf16 v[88:91], v[184:187], v[202:205], v[88:91]
	v_mfma_f32_16x16x32_bf16 v[92:95], v[194:197], v[202:205], v[92:95]
	v_mfma_f32_16x16x32_bf16 v[80:83], v[184:187], v[214:217], v[80:83]
	v_mfma_f32_16x16x32_bf16 v[84:87], v[194:197], v[214:217], v[84:87]
	v_mfma_f32_16x16x32_bf16 v[72:75], v[184:187], v[222:225], v[72:75]
	v_mfma_f32_16x16x32_bf16 v[76:79], v[194:197], v[222:225], v[76:79]
	v_mfma_f32_16x16x32_bf16 v[64:67], v[184:187], v[230:233], v[64:67]
	v_mfma_f32_16x16x32_bf16 v[68:71], v[194:197], v[230:233], v[68:71]
	s_setprio 0
	s_barrier
; __device__ __forceinline__ float bflo(unsigned w) { return __uint_as_float(w << 16); }
; __device__ __forceinline__ float bfhi(unsigned w) { return __uint_as_float(w & 0xffff0000u); }
; #define PG8_STAGE(bufoff, gbase, voff) do { _Pragma("unroll") for (int _i = 0; _i < 2; ++_i) \
;         __builtin_amdgcn_global_load_lds((const unsigned*)((const char*)(gbase) + (voff)[_i]), (PG8_LAS unsigned*)(lds + (bufoff) + ldsw + _i * 8192), 16, 0, 0); } while (0)
; #define PG8_LDA(dst, b, h) do { _Pragma("unroll") for (int m = 0; m < 4; ++m) _Pragma("unroll") for (int k = 0; k < 2; ++k) dst[m][k] = *(const PG8_LAS bf16x8*)(lds + PG8_SA(b, h) + aoff + m * 2048 + k * 1024); } while (0)
; #define PG8_WAIT_V(n) asm volatile("s_waitcnt vmcnt(" #n ")" ::: "memory")
; #define PG8_WAIT_L(n) asm volatile("s_waitcnt lgkmcnt(" #n ")" ::: "memory")
; #define PG8_BAR __builtin_amdgcn_s_barrier()
;     __device__ __forceinline__ void mid(f32x4 (&acc)[2][2][4][2], const Unit& u, int wr, int wc, int fr, int fq) const {
;         int row0 = u.pm * BM + wr * 64 + fr, col0 = u.pn * BM + wc * 32 + 8 * fq;
;         asm volatile("" : "+v"(row0), "+v"(col0) :: "memory");
; #pragma unroll
;         for (int ai = 0; ai < 2; ++ai)
; #pragma unroll
;             for (int m = 0; m < 4; ++m) {
;                 int roff = row0 + ai * HALF + m * 16; asm volatile("" : "+v"(roff) :: "memory"); const bf16_t* gp = gates + (size_t)roff * 4096 + col0;
; #pragma unroll
;                 for (int bj = 0; bj < 2; ++bj) { const u32x4 a = __builtin_nontemporal_load((const u32x4*)(gp + bj * HALF));
;                     f32x4 r0, r1;
;                     r0[0] = bflo(a[0]); r0[1] = bfhi(a[0]); r0[2] = bflo(a[1]); r0[3] = bfhi(a[1]); r1[0] = bflo(a[2]); r1[1] = bfhi(a[2]); r1[2] = bflo(a[3]); r1[3] = bfhi(a[3]);
;                     acc[ai][bj][m][0] = acc[ai][bj][m][0] * r0; acc[ai][bj][m][1] = acc[ai][bj][m][1] * r1; }
; template <class Epi, class Sched, bool ALIGN_EPI = false, bool SP2 = false>
; __device__ __forceinline__ void gemm_phase(PG8_LAS unsigned char* lds, const Gemm g, const Sched& S, const Epi& E) {
;     ...
;             PG8_LDA(At, 1, 1); PG8_STAGE(PG8_SB(1, 0), b3, voffB); PG8_STAGE(PG8_SB(1, 1), b3 + hstep, voffB); PG8_STAGE(PG8_SA(1, 0), a3, voffA);
;             PG8_WAIT_V(8); PG8_WAIT_L(0); PG8_BAR; PG8_MMA(1, 0, At, B0); PG8_MMA(1, 1, At, B1); PG8_BAR; PG8_SCHED;
	s_add_i32 s82, s75, s23
	v_lshl_add_u64 v[240:241], v[236:237], 0, s[40:41]
	s_mov_b32 m0, s82
	s_add_i32 s83, s82, 0x2000
	ds_read_b128 v[198:201], v161 offset:49152
	ds_read_b128 v[202:205], v161 offset:50176
	ds_read_b128 v[206:209], v161 offset:51200
	ds_read_b128 v[214:217], v161 offset:52224
	ds_read_b128 v[218:221], v161 offset:53248
	ds_read_b128 v[222:225], v161 offset:54272
	ds_read_b128 v[226:229], v161 offset:55296
	ds_read_b128 v[230:233], v161 offset:56320
	global_load_lds_dwordx4 v[240:241], off
	v_lshl_add_u64 v[240:241], v[238:239], 0, s[40:41]
	s_mov_b32 m0, s83
	s_add_i32 s85, s84, s23
	global_load_lds_dwordx4 v[240:241], off
	v_lshl_add_u64 v[236:237], v[236:237], 0, s[46:47]
	s_mov_b32 m0, s85
	s_add_i32 s86, s85, 0x2000
	global_load_lds_dwordx4 v[236:237], off
	v_lshl_add_u64 v[236:237], v[238:239], 0, s[46:47]
	s_mov_b32 m0, s86
	v_lshl_add_u64 v[210:211], v[210:211], 0, s[40:41]
	global_load_lds_dwordx4 v[236:237], off
	s_mov_b32 m0, s71
	s_nop 0
	global_load_lds_dwordx4 v[210:211], off
	v_lshl_add_u64 v[210:211], v[234:235], 0, s[40:41]
	s_mov_b32 m0, s76
	s_nop 0
	global_load_lds_dwordx4 v[210:211], off
	s_waitcnt vmcnt(8)
	s_waitcnt lgkmcnt(0)
	s_barrier
	s_setprio 1
	s_waitcnt lgkmcnt(0)
	v_mfma_f32_16x16x32_bf16 v[60:63], v[164:167], v[198:201], v[60:63]
	v_mfma_f32_16x16x32_bf16 v[56:59], v[172:175], v[198:201], v[56:59]
	v_mfma_f32_16x16x32_bf16 v[44:47], v[164:167], v[206:209], v[44:47]
	v_mfma_f32_16x16x32_bf16 v[40:43], v[172:175], v[206:209], v[40:43]
	v_mfma_f32_16x16x32_bf16 v[28:31], v[164:167], v[218:221], v[28:31]
	v_mfma_f32_16x16x32_bf16 v[24:27], v[172:175], v[218:221], v[24:27]
	v_mfma_f32_16x16x32_bf16 v[12:15], v[164:167], v[226:229], v[12:15]
	v_mfma_f32_16x16x32_bf16 v[8:11], v[172:175], v[226:229], v[8:11]
	v_mfma_f32_16x16x32_bf16 v[60:63], v[168:171], v[202:205], v[60:63]
	v_mfma_f32_16x16x32_bf16 v[56:59], v[176:179], v[202:205], v[56:59]
	v_mfma_f32_16x16x32_bf16 v[44:47], v[168:171], v[214:217], v[44:47]
	v_mfma_f32_16x16x32_bf16 v[40:43], v[176:179], v[214:217], v[40:43]
	v_mfma_f32_16x16x32_bf16 v[28:31], v[168:171], v[222:225], v[28:31]
	v_mfma_f32_16x16x32_bf16 v[24:27], v[176:179], v[222:225], v[24:27]
	v_mfma_f32_16x16x32_bf16 v[12:15], v[168:171], v[230:233], v[12:15]
	v_mfma_f32_16x16x32_bf16 v[8:11], v[176:179], v[230:233], v[8:11]
	s_setprio 0
	s_setprio 1
	v_mfma_f32_16x16x32_bf16 v[52:55], v[180:183], v[198:201], v[52:55]
	v_mfma_f32_16x16x32_bf16 v[48:51], v[190:193], v[198:201], v[48:51]
	v_mfma_f32_16x16x32_bf16 v[36:39], v[180:183], v[206:209], v[36:39]
	v_mfma_f32_16x16x32_bf16 v[32:35], v[190:193], v[206:209], v[32:35]
	v_mfma_f32_16x16x32_bf16 v[20:23], v[180:183], v[218:221], v[20:23]
	v_mfma_f32_16x16x32_bf16 v[16:19], v[190:193], v[218:221], v[16:19]
	v_mfma_f32_16x16x32_bf16 v[4:7], v[180:183], v[226:229], v[4:7]
	v_mfma_f32_16x16x32_bf16 v[0:3], v[190:193], v[226:229], v[0:3]
	v_mfma_f32_16x16x32_bf16 v[52:55], v[184:187], v[202:205], v[52:55]
	v_mfma_f32_16x16x32_bf16 v[48:51], v[194:197], v[202:205], v[48:51]
	v_mfma_f32_16x16x32_bf16 v[36:39], v[184:187], v[214:217], v[36:39]
	v_mfma_f32_16x16x32_bf16 v[32:35], v[194:197], v[214:217], v[32:35]
	v_mfma_f32_16x16x32_bf16 v[20:23], v[184:187], v[222:225], v[20:23]
	v_mfma_f32_16x16x32_bf16 v[16:19], v[194:197], v[222:225], v[16:19]
	v_mfma_f32_16x16x32_bf16 v[4:7], v[184:187], v[230:233], v[4:7]
	v_mfma_f32_16x16x32_bf16 v[0:3], v[194:197], v[230:233], v[0:3]
	s_setprio 0
	s_barrier
	s_add_i32 s59, s59, 2
	s_add_u32 s64, s64, 0x100
	s_addc_u32 s65, s65, 0
	s_cmp_gt_u32 s59, 13
	s_cbranch_scc0 .LBB0_703
	v_lshl_add_u32 v148, s68, 8, v156
	v_lshl_or_b32 v150, s57, 8, v158
	v_ashrrev_i32_e32 v153, 31, v148
	v_mov_b32_e32 v152, v148
	v_ashrrev_i32_e32 v155, 31, v150
	v_mov_b32_e32 v154, v150
	v_lshlrev_b64 v[152:153], 13, v[152:153]
	v_lshlrev_b64 v[154:155], 1, v[154:155]
	v_lshl_add_u64 v[152:153], s[18:19], 0, v[152:153]
	v_lshl_add_u64 v[152:153], v[152:153], 0, v[154:155]
	s_mov_b64 s[64:65], 0x20000
	s_mov_b64 s[66:67], 0xa0000
	global_load_dwordx4 v[164:167], v[152:153], off nt
	global_load_dwordx4 v[168:171], v[152:153], off offset:256 nt
	v_lshl_add_u64 v[152:153], v[152:153], 0, s[64:65]
	global_load_dwordx4 v[172:175], v[152:153], off nt
	global_load_dwordx4 v[176:179], v[152:153], off offset:256 nt
	v_lshl_add_u64 v[152:153], v[152:153], 0, s[64:65]
	global_load_dwordx4 v[180:183], v[152:153], off nt
	global_load_dwordx4 v[184:187], v[152:153], off offset:256 nt
	v_lshl_add_u64 v[152:153], v[152:153], 0, s[64:65]
	global_load_dwordx4 v[190:193], v[152:153], off nt
	global_load_dwordx4 v[194:197], v[152:153], off offset:256 nt
	v_lshl_add_u64 v[152:153], v[152:153], 0, s[66:67]
	global_load_dwordx4 v[198:201], v[152:153], off nt
	global_load_dwordx4 v[202:205], v[152:153], off offset:256 nt
	v_lshl_add_u64 v[152:153], v[152:153], 0, s[64:65]
	global_load_dwordx4 v[206:209], v[152:153], off nt
	global_load_dwordx4 v[214:217], v[152:153], off offset:256 nt
	v_lshl_add_u64 v[152:153], v[152:153], 0, s[64:65]
	global_load_dwordx4 v[218:221], v[152:153], off nt
	global_load_dwordx4 v[222:225], v[152:153], off offset:256 nt
	v_lshl_add_u64 v[152:153], v[152:153], 0, s[64:65]
	global_load_dwordx4 v[226:229], v[152:153], off nt
	global_load_dwordx4 v[230:233], v[152:153], off offset:256 nt
	s_ashr_i32 s59, s58, 31
	s_lshl_b64 s[64:65], s[58:59], 20
	s_add_u32 s64, s72, s64
	s_addc_u32 s65, s73, s65
	s_ashr_i32 s57, s56, 31
	s_lshl_b64 s[66:67], s[56:57], 20
	s_add_u32 s66, s88, s66
	s_addc_u32 s67, s89, s67
	s_and_b64 s[68:69], s[2:3], exec
	s_cselect_b32 s57, s65, s63
	s_cselect_b32 s59, s64, s62
	s_cselect_b32 s87, s67, s61
	s_cselect_b32 s90, s66, s60
	s_waitcnt vmcnt(15)
; __device__ __forceinline__ float bflo(unsigned w) { return __uint_as_float(w << 16); }
; __device__ __forceinline__ float bfhi(unsigned w) { return __uint_as_float(w & 0xffff0000u); }
;     __device__ __forceinline__ void mid(f32x4 (&acc)[2][2][4][2], const Unit& u, int wr, int wc, int fr, int fq) const {
;     ...
;                 int roff = row0 + ai * HALF + m * 16; asm volatile("" : "+v"(roff) :: "memory"); const bf16_t* gp = gates + (size_t)roff * 4096 + col0;
; #pragma unroll
;                 for (int bj = 0; bj < 2; ++bj) { const u32x4 a = __builtin_nontemporal_load((const u32x4*)(gp + bj * HALF));
;                     f32x4 r0, r1;
;                     r0[0] = bflo(a[0]); r0[1] = bfhi(a[0]); r0[2] = bflo(a[1]); r0[3] = bfhi(a[1]); r1[0] = bflo(a[2]); r1[1] = bfhi(a[2]); r1[2] = bflo(a[3]); r1[3] = bfhi(a[3]);
;                     acc[ai][bj][m][0] = acc[ai][bj][m][0] * r0; acc[ai][bj][m][1] = acc[ai][bj][m][1] * r1; }
	v_lshlrev_b32_e32 v234, 16, v164
	v_and_b32_e32 v235, 0xffff0000, v164
	v_lshlrev_b32_e32 v164, 16, v165
	v_and_b32_e32 v165, 0xffff0000, v165
	v_lshlrev_b32_e32 v236, 16, v166
	v_and_b32_e32 v237, 0xffff0000, v166
	v_lshlrev_b32_e32 v166, 16, v167
	v_and_b32_e32 v167, 0xffff0000, v167
	v_pk_mul_f32 v[124:125], v[124:125], v[234:235]
	v_pk_mul_f32 v[126:127], v[126:127], v[164:165]
	v_pk_mul_f32 v[120:121], v[120:121], v[236:237]
	v_pk_mul_f32 v[122:123], v[122:123], v[166:167]
	s_waitcnt vmcnt(14)
	v_lshlrev_b32_e32 v238, 16, v168
	v_and_b32_e32 v239, 0xffff0000, v168
	v_lshlrev_b32_e32 v168, 16, v169
	v_and_b32_e32 v169, 0xffff0000, v169
	v_lshlrev_b32_e32 v240, 16, v170
	v_and_b32_e32 v241, 0xffff0000, v170
	v_lshlrev_b32_e32 v170, 16, v171
	v_and_b32_e32 v171, 0xffff0000, v171
	v_pk_mul_f32 v[88:89], v[88:89], v[238:239]
	v_pk_mul_f32 v[90:91], v[90:91], v[168:169]
	v_pk_mul_f32 v[92:93], v[92:93], v[240:241]
	v_pk_mul_f32 v[94:95], v[94:95], v[170:171]
	s_waitcnt vmcnt(13)
	v_lshlrev_b32_e32 v234, 16, v172
	v_and_b32_e32 v235, 0xffff0000, v172
	v_lshlrev_b32_e32 v172, 16, v173
	v_and_b32_e32 v173, 0xffff0000, v173
	v_lshlrev_b32_e32 v236, 16, v174
	v_and_b32_e32 v237, 0xffff0000, v174
	v_lshlrev_b32_e32 v174, 16, v175
	v_and_b32_e32 v175, 0xffff0000, v175
	v_pk_mul_f32 v[116:117], v[116:117], v[234:235]
	v_pk_mul_f32 v[118:119], v[118:119], v[172:173]
	v_pk_mul_f32 v[112:113], v[112:113], v[236:237]
	v_pk_mul_f32 v[114:115], v[114:115], v[174:175]
	s_waitcnt vmcnt(12)
	v_lshlrev_b32_e32 v238, 16, v176
	v_and_b32_e32 v239, 0xffff0000, v176
	v_lshlrev_b32_e32 v176, 16, v177
	v_and_b32_e32 v177, 0xffff0000, v177
	v_lshlrev_b32_e32 v240, 16, v178
	v_and_b32_e32 v241, 0xffff0000, v178
	v_lshlrev_b32_e32 v178, 16, v179
	v_and_b32_e32 v179, 0xffff0000, v179
	v_pk_mul_f32 v[80:81], v[80:81], v[238:239]
	v_pk_mul_f32 v[82:83], v[82:83], v[176:177]
	v_pk_mul_f32 v[84:85], v[84:85], v[240:241]
	v_pk_mul_f32 v[86:87], v[86:87], v[178:179]
	s_waitcnt vmcnt(11)
	v_lshlrev_b32_e32 v234, 16, v180
	v_and_b32_e32 v235, 0xffff0000, v180
	v_lshlrev_b32_e32 v180, 16, v181
	v_and_b32_e32 v181, 0xffff0000, v181
	v_lshlrev_b32_e32 v236, 16, v182
	v_and_b32_e32 v237, 0xffff0000, v182
	v_lshlrev_b32_e32 v182, 16, v183
	v_and_b32_e32 v183, 0xffff0000, v183
	v_pk_mul_f32 v[108:109], v[108:109], v[234:235]
	v_pk_mul_f32 v[110:111], v[110:111], v[180:181]
	v_pk_mul_f32 v[104:105], v[104:105], v[236:237]
	v_pk_mul_f32 v[106:107], v[106:107], v[182:183]
	s_waitcnt vmcnt(10)
	v_lshlrev_b32_e32 v238, 16, v184
	v_and_b32_e32 v239, 0xffff0000, v184
	v_lshlrev_b32_e32 v184, 16, v185
	v_and_b32_e32 v185, 0xffff0000, v185
	v_lshlrev_b32_e32 v240, 16, v186
	v_and_b32_e32 v241, 0xffff0000, v186
	v_lshlrev_b32_e32 v186, 16, v187
	v_and_b32_e32 v187, 0xffff0000, v187
	v_pk_mul_f32 v[72:73], v[72:73], v[238:239]
	v_pk_mul_f32 v[74:75], v[74:75], v[184:185]
	v_pk_mul_f32 v[76:77], v[76:77], v[240:241]
	v_pk_mul_f32 v[78:79], v[78:79], v[186:187]
	s_waitcnt vmcnt(9)
	v_lshlrev_b32_e32 v234, 16, v190
	v_and_b32_e32 v235, 0xffff0000, v190
	v_lshlrev_b32_e32 v190, 16, v191
	v_and_b32_e32 v191, 0xffff0000, v191
	v_lshlrev_b32_e32 v236, 16, v192
	v_and_b32_e32 v237, 0xffff0000, v192
	v_lshlrev_b32_e32 v192, 16, v193
	v_and_b32_e32 v193, 0xffff0000, v193
	v_pk_mul_f32 v[100:101], v[100:101], v[234:235]
	v_pk_mul_f32 v[102:103], v[102:103], v[190:191]
	v_pk_mul_f32 v[96:97], v[96:97], v[236:237]
	v_pk_mul_f32 v[98:99], v[98:99], v[192:193]
	s_waitcnt vmcnt(8)
	v_lshlrev_b32_e32 v238, 16, v194
	v_and_b32_e32 v239, 0xffff0000, v194
	v_lshlrev_b32_e32 v194, 16, v195
	v_and_b32_e32 v195, 0xffff0000, v195
	v_lshlrev_b32_e32 v240, 16, v196
	v_and_b32_e32 v241, 0xffff0000, v196
	v_lshlrev_b32_e32 v196, 16, v197
	v_and_b32_e32 v197, 0xffff0000, v197
	v_pk_mul_f32 v[64:65], v[64:65], v[238:239]
	v_pk_mul_f32 v[66:67], v[66:67], v[194:195]
	v_pk_mul_f32 v[68:69], v[68:69], v[240:241]
	v_pk_mul_f32 v[70:71], v[70:71], v[196:197]
	s_waitcnt vmcnt(7)
; __device__ __forceinline__ float bflo(unsigned w) { return __uint_as_float(w << 16); }
; __device__ __forceinline__ float bfhi(unsigned w) { return __uint_as_float(w & 0xffff0000u); }
;     __device__ __forceinline__ void mid(f32x4 (&acc)[2][2][4][2], const Unit& u, int wr, int wc, int fr, int fq) const {
;     ...
;             for (int m = 0; m < 4; ++m) {
;                 int roff = row0 + ai * HALF + m * 16; asm volatile("" : "+v"(roff) :: "memory"); const bf16_t* gp = gates + (size_t)roff * 4096 + col0;
; #pragma unroll
;                 for (int bj = 0; bj < 2; ++bj) { const u32x4 a = __builtin_nontemporal_load((const u32x4*)(gp + bj * HALF));
;                     f32x4 r0, r1;
;                     r0[0] = bflo(a[0]); r0[1] = bfhi(a[0]); r0[2] = bflo(a[1]); r0[3] = bfhi(a[1]); r1[0] = bflo(a[2]); r1[1] = bfhi(a[2]); r1[2] = bflo(a[3]); r1[3] = bfhi(a[3]);
;                     acc[ai][bj][m][0] = acc[ai][bj][m][0] * r0; acc[ai][bj][m][1] = acc[ai][bj][m][1] * r1; }
;                 asm volatile("" : "+v"(acc[ai][0][m][0]), "+v"(acc[ai][0][m][1]), "+v"(acc[ai][1][m][0]), "+v"(acc[ai][1][m][1]));
;                 __builtin_amdgcn_sched_barrier(0);
;             }
	v_lshlrev_b32_e32 v234, 16, v198
	v_and_b32_e32 v235, 0xffff0000, v198
	v_lshlrev_b32_e32 v198, 16, v199
	v_and_b32_e32 v199, 0xffff0000, v199
	v_lshlrev_b32_e32 v236, 16, v200
	v_and_b32_e32 v237, 0xffff0000, v200
	v_lshlrev_b32_e32 v200, 16, v201
	v_and_b32_e32 v201, 0xffff0000, v201
	v_pk_mul_f32 v[60:61], v[60:61], v[234:235]
	v_pk_mul_f32 v[62:63], v[62:63], v[198:199]
	v_pk_mul_f32 v[56:57], v[56:57], v[236:237]
	v_pk_mul_f32 v[58:59], v[58:59], v[200:201]
	s_waitcnt vmcnt(6)
	v_lshlrev_b32_e32 v238, 16, v202
	v_and_b32_e32 v239, 0xffff0000, v202
	v_lshlrev_b32_e32 v202, 16, v203
	v_and_b32_e32 v203, 0xffff0000, v203
	v_lshlrev_b32_e32 v240, 16, v204
	v_and_b32_e32 v241, 0xffff0000, v204
	v_lshlrev_b32_e32 v204, 16, v205
	v_and_b32_e32 v205, 0xffff0000, v205
	v_pk_mul_f32 v[52:53], v[52:53], v[238:239]
	v_pk_mul_f32 v[54:55], v[54:55], v[202:203]
	v_pk_mul_f32 v[48:49], v[48:49], v[240:241]
	v_pk_mul_f32 v[50:51], v[50:51], v[204:205]
	s_waitcnt vmcnt(5)
	v_lshlrev_b32_e32 v234, 16, v206
	v_and_b32_e32 v235, 0xffff0000, v206
	v_lshlrev_b32_e32 v206, 16, v207
	v_and_b32_e32 v207, 0xffff0000, v207
	v_lshlrev_b32_e32 v236, 16, v208
	v_and_b32_e32 v237, 0xffff0000, v208
	v_lshlrev_b32_e32 v208, 16, v209
	v_and_b32_e32 v209, 0xffff0000, v209
	v_pk_mul_f32 v[44:45], v[44:45], v[234:235]
	v_pk_mul_f32 v[46:47], v[46:47], v[206:207]
	v_pk_mul_f32 v[40:41], v[40:41], v[236:237]
	v_pk_mul_f32 v[42:43], v[42:43], v[208:209]
	s_waitcnt vmcnt(4)
	v_lshlrev_b32_e32 v238, 16, v214
	v_and_b32_e32 v239, 0xffff0000, v214
	v_lshlrev_b32_e32 v214, 16, v215
	v_and_b32_e32 v215, 0xffff0000, v215
	v_lshlrev_b32_e32 v240, 16, v216
	v_and_b32_e32 v241, 0xffff0000, v216
	v_lshlrev_b32_e32 v216, 16, v217
	v_and_b32_e32 v217, 0xffff0000, v217
	v_pk_mul_f32 v[36:37], v[36:37], v[238:239]
	v_pk_mul_f32 v[38:39], v[38:39], v[214:215]
	v_pk_mul_f32 v[32:33], v[32:33], v[240:241]
	v_pk_mul_f32 v[34:35], v[34:35], v[216:217]
	s_waitcnt vmcnt(3)
	v_lshlrev_b32_e32 v234, 16, v218
	v_and_b32_e32 v235, 0xffff0000, v218
	v_lshlrev_b32_e32 v218, 16, v219
	v_and_b32_e32 v219, 0xffff0000, v219
	v_lshlrev_b32_e32 v236, 16, v220
	v_and_b32_e32 v237, 0xffff0000, v220
	v_lshlrev_b32_e32 v220, 16, v221
	v_and_b32_e32 v221, 0xffff0000, v221
	v_pk_mul_f32 v[28:29], v[28:29], v[234:235]
	v_pk_mul_f32 v[30:31], v[30:31], v[218:219]
	v_pk_mul_f32 v[24:25], v[24:25], v[236:237]
	v_pk_mul_f32 v[26:27], v[26:27], v[220:221]
	s_waitcnt vmcnt(2)
	v_lshlrev_b32_e32 v238, 16, v222
	v_and_b32_e32 v239, 0xffff0000, v222
	v_lshlrev_b32_e32 v222, 16, v223
	v_and_b32_e32 v223, 0xffff0000, v223
	v_lshlrev_b32_e32 v240, 16, v224
	v_and_b32_e32 v241, 0xffff0000, v224
	v_lshlrev_b32_e32 v224, 16, v225
	v_and_b32_e32 v225, 0xffff0000, v225
	v_pk_mul_f32 v[20:21], v[20:21], v[238:239]
	v_pk_mul_f32 v[22:23], v[22:23], v[222:223]
	v_pk_mul_f32 v[16:17], v[16:17], v[240:241]
	v_pk_mul_f32 v[18:19], v[18:19], v[224:225]
	s_waitcnt vmcnt(1)
	v_lshlrev_b32_e32 v234, 16, v226
	v_and_b32_e32 v235, 0xffff0000, v226
	v_lshlrev_b32_e32 v226, 16, v227
	v_and_b32_e32 v227, 0xffff0000, v227
	v_lshlrev_b32_e32 v236, 16, v228
	v_and_b32_e32 v237, 0xffff0000, v228
	v_lshlrev_b32_e32 v228, 16, v229
	v_and_b32_e32 v229, 0xffff0000, v229
	v_pk_mul_f32 v[12:13], v[12:13], v[234:235]
	v_pk_mul_f32 v[14:15], v[14:15], v[226:227]
	v_pk_mul_f32 v[8:9], v[8:9], v[236:237]
	v_pk_mul_f32 v[10:11], v[10:11], v[228:229]
	s_waitcnt vmcnt(0)
	v_lshlrev_b32_e32 v238, 16, v230
	v_and_b32_e32 v239, 0xffff0000, v230
	v_lshlrev_b32_e32 v230, 16, v231
	v_and_b32_e32 v231, 0xffff0000, v231
	v_lshlrev_b32_e32 v240, 16, v232
	v_and_b32_e32 v241, 0xffff0000, v232
	v_lshlrev_b32_e32 v232, 16, v233
	v_and_b32_e32 v233, 0xffff0000, v233
	v_pk_mul_f32 v[4:5], v[4:5], v[238:239]
	v_pk_mul_f32 v[6:7], v[6:7], v[230:231]
	v_pk_mul_f32 v[0:1], v[0:1], v[240:241]
	v_pk_mul_f32 v[2:3], v[2:3], v[232:233]
	s_add_u32 s62, s62, 0x80880
	s_addc_u32 s63, s63, 0
	s_add_u32 s91, s60, 0x900
	s_addc_u32 s92, s61, 0
	s_mov_b32 s93, 14

; __device__ __forceinline__ unsigned cvt_pk_bf16(float lo, float hi) { unsigned r; asm volatile("v_cvt_pk_bf16_f32 %0, %1, %2" : "=v"(r) : "v"(lo), "v"(hi)); return r; }
; __device__ __forceinline__ float bflo(unsigned w) { return __uint_as_float(w << 16); }
; __device__ __forceinline__ float bfhi(unsigned w) { return __uint_as_float(w & 0xffff0000u); }
;     __device__ __forceinline__ void operator()(const f32x4 (&acc)[2][2][4][2], const Unit& u, int wr, int wc, int fr, int fq) const {
;         const int row0 = u.pm * BM + wr * 64 + fr, col0 = u.pn * BM + wc * 32 + 8 * fq;
; #pragma unroll
;         for (int ai = 0; ai < 2; ++ai)
; #pragma unroll
;             for (int m = 0; m < 4; ++m) { const size_t r = (size_t)(row0 + ai * HALF + m * 16);
; #pragma unroll
;                 for (int bj = 0; bj < 2; ++bj) { const u32x4 b = *(const u32x4*)(gates + r * 4096 + 2048 + col0 + bj * HALF);
;                     const f32x4 v0 = acc[ai][bj][m][0], v1 = acc[ai][bj][m][1];
;                     u32x4 w; w.x = cvt_pk_bf16(v0[0] * bflo(b[0]), v0[1] * bfhi(b[0])); w.y = cvt_pk_bf16(v0[2] * bflo(b[1]), v0[3] * bfhi(b[1]));
;                     w.z = cvt_pk_bf16(v1[0] * bflo(b[2]), v1[1] * bfhi(b[2])); w.w = cvt_pk_bf16(v1[2] * bflo(b[3]), v1[3] * bfhi(b[3]));
;                     *(u32x4*)(O + r * 2048 + col0 + bj * HALF) = w; }
;                 asm volatile("" ::: "memory"); }
;     }
.LBB0_708:
	v_ashrrev_i32_e32 v149, 31, v148
	v_ashrrev_i32_e32 v151, 31, v150
	v_lshlrev_b64 v[152:153], 13, v[148:149]
	v_lshl_add_u64 v[152:153], s[18:19], 0, v[152:153]
	v_lshlrev_b64 v[150:151], 1, v[150:151]
	v_lshl_add_u64 v[152:153], v[152:153], 0, v[150:151]
	s_mov_b64 s[0:1], 0x1000
	v_lshl_add_u64 v[162:163], v[152:153], 0, s[0:1]
	v_lshlrev_b64 v[154:155], 12, v[148:149]
	v_lshl_add_u64 v[154:155], s[54:55], 0, v[154:155]
	v_lshl_add_u64 v[154:155], v[154:155], 0, v[150:151]
	global_load_dwordx4 v[164:167], v[162:163], off
	global_load_dwordx4 v[168:171], v[162:163], off offset:256
	s_mov_b64 s[0:1], 0x20000
	v_lshl_add_u64 v[162:163], v[162:163], 0, s[0:1]
	global_load_dwordx4 v[172:175], v[162:163], off
	global_load_dwordx4 v[176:179], v[162:163], off offset:256
	s_mov_b64 s[0:1], 0x20000
	v_lshl_add_u64 v[162:163], v[162:163], 0, s[0:1]
	global_load_dwordx4 v[180:183], v[162:163], off
	global_load_dwordx4 v[184:187], v[162:163], off offset:256
	s_mov_b64 s[0:1], 0x20000
	v_lshl_add_u64 v[162:163], v[162:163], 0, s[0:1]
	global_load_dwordx4 v[190:193], v[162:163], off
	global_load_dwordx4 v[194:197], v[162:163], off offset:256
	s_mov_b64 s[0:1], 0xa0000
	v_lshl_add_u64 v[162:163], v[162:163], 0, s[0:1]
	global_load_dwordx4 v[198:201], v[162:163], off
	global_load_dwordx4 v[202:205], v[162:163], off offset:256
	s_mov_b64 s[0:1], 0x20000
	v_lshl_add_u64 v[162:163], v[162:163], 0, s[0:1]
	global_load_dwordx4 v[206:209], v[162:163], off
	global_load_dwordx4 v[214:217], v[162:163], off offset:256
	s_mov_b64 s[0:1], 0x20000
	v_lshl_add_u64 v[162:163], v[162:163], 0, s[0:1]
	global_load_dwordx4 v[218:221], v[162:163], off
	global_load_dwordx4 v[222:225], v[162:163], off offset:256
	s_mov_b64 s[0:1], 0x20000
	v_lshl_add_u64 v[162:163], v[162:163], 0, s[0:1]
	global_load_dwordx4 v[226:229], v[162:163], off
	global_load_dwordx4 v[230:233], v[162:163], off offset:256
	s_waitcnt vmcnt(15)
	v_lshlrev_b32_e32 v234, 16, v164
	v_and_b32_e32 v235, 0xffff0000, v164
	v_lshlrev_b32_e32 v164, 16, v165
	v_and_b32_e32 v165, 0xffff0000, v165
	v_lshlrev_b32_e32 v236, 16, v166
	v_and_b32_e32 v237, 0xffff0000, v166
	v_lshlrev_b32_e32 v166, 16, v167
	v_and_b32_e32 v167, 0xffff0000, v167
	v_pk_mul_f32 v[124:125], v[124:125], v[234:235]
	v_pk_mul_f32 v[126:127], v[126:127], v[164:165]
	v_pk_mul_f32 v[120:121], v[120:121], v[236:237]
	v_pk_mul_f32 v[122:123], v[122:123], v[166:167]
	v_cvt_pk_bf16_f32 v124, v124, v125
	v_cvt_pk_bf16_f32 v125, v126, v127
	v_cvt_pk_bf16_f32 v126, v120, v121
	v_cvt_pk_bf16_f32 v127, v122, v123
	global_store_dwordx4 v[154:155], v[124:127], off
	s_waitcnt vmcnt(15)
	v_lshlrev_b32_e32 v238, 16, v168
	v_and_b32_e32 v239, 0xffff0000, v168
	v_lshlrev_b32_e32 v168, 16, v169
	v_and_b32_e32 v169, 0xffff0000, v169
	v_lshlrev_b32_e32 v240, 16, v170
	v_and_b32_e32 v241, 0xffff0000, v170
	v_lshlrev_b32_e32 v170, 16, v171
	v_and_b32_e32 v171, 0xffff0000, v171
	v_pk_mul_f32 v[88:89], v[88:89], v[238:239]
	v_pk_mul_f32 v[90:91], v[90:91], v[168:169]
	v_pk_mul_f32 v[92:93], v[92:93], v[240:241]
	v_pk_mul_f32 v[94:95], v[94:95], v[170:171]
	v_cvt_pk_bf16_f32 v88, v88, v89
	v_cvt_pk_bf16_f32 v89, v90, v91
	v_cvt_pk_bf16_f32 v90, v92, v93
	v_cvt_pk_bf16_f32 v91, v94, v95
	global_store_dwordx4 v[154:155], v[88:91], off offset:256
	s_mov_b64 s[0:1], 0x10000
	v_lshl_add_u64 v[154:155], v[154:155], 0, s[0:1]
	s_waitcnt vmcnt(15)
	v_lshlrev_b32_e32 v234, 16, v172
	v_and_b32_e32 v235, 0xffff0000, v172
	v_lshlrev_b32_e32 v172, 16, v173
	v_and_b32_e32 v173, 0xffff0000, v173
	v_lshlrev_b32_e32 v236, 16, v174
	v_and_b32_e32 v237, 0xffff0000, v174
	v_lshlrev_b32_e32 v174, 16, v175
	v_and_b32_e32 v175, 0xffff0000, v175
	v_pk_mul_f32 v[116:117], v[116:117], v[234:235]
	v_pk_mul_f32 v[118:119], v[118:119], v[172:173]
	v_pk_mul_f32 v[112:113], v[112:113], v[236:237]
	v_pk_mul_f32 v[114:115], v[114:115], v[174:175]
	v_cvt_pk_bf16_f32 v116, v116, v117
	v_cvt_pk_bf16_f32 v117, v118, v119
	v_cvt_pk_bf16_f32 v118, v112, v113
	v_cvt_pk_bf16_f32 v119, v114, v115
	global_store_dwordx4 v[154:155], v[116:119], off
	s_waitcnt vmcnt(15)
	v_lshlrev_b32_e32 v238, 16, v176
	v_and_b32_e32 v239, 0xffff0000, v176
	v_lshlrev_b32_e32 v176, 16, v177
	v_and_b32_e32 v177, 0xffff0000, v177
	v_lshlrev_b32_e32 v240, 16, v178
	v_and_b32_e32 v241, 0xffff0000, v178
	v_lshlrev_b32_e32 v178, 16, v179
	v_and_b32_e32 v179, 0xffff0000, v179
	v_pk_mul_f32 v[80:81], v[80:81], v[238:239]
	v_pk_mul_f32 v[82:83], v[82:83], v[176:177]
	v_pk_mul_f32 v[84:85], v[84:85], v[240:241]
	v_pk_mul_f32 v[86:87], v[86:87], v[178:179]
	v_cvt_pk_bf16_f32 v80, v80, v81
	v_cvt_pk_bf16_f32 v81, v82, v83
	v_cvt_pk_bf16_f32 v82, v84, v85
	v_cvt_pk_bf16_f32 v83, v86, v87
	global_store_dwordx4 v[154:155], v[80:83], off offset:256
	s_mov_b64 s[0:1], 0x10000
	v_lshl_add_u64 v[154:155], v[154:155], 0, s[0:1]
	s_waitcnt vmcnt(15)
	v_lshlrev_b32_e32 v234, 16, v180
	v_and_b32_e32 v235, 0xffff0000, v180
	v_lshlrev_b32_e32 v180, 16, v181
	v_and_b32_e32 v181, 0xffff0000, v181
	v_lshlrev_b32_e32 v236, 16, v182
	v_and_b32_e32 v237, 0xffff0000, v182
	v_lshlrev_b32_e32 v182, 16, v183
	v_and_b32_e32 v183, 0xffff0000, v183
	v_pk_mul_f32 v[108:109], v[108:109], v[234:235]
	v_pk_mul_f32 v[110:111], v[110:111], v[180:181]
	v_pk_mul_f32 v[104:105], v[104:105], v[236:237]
	v_pk_mul_f32 v[106:107], v[106:107], v[182:183]
	v_cvt_pk_bf16_f32 v108, v108, v109
	v_cvt_pk_bf16_f32 v109, v110, v111
	v_cvt_pk_bf16_f32 v110, v104, v105
	v_cvt_pk_bf16_f32 v111, v106, v107
	global_store_dwordx4 v[154:155], v[108:111], off
	s_waitcnt vmcnt(15)
; __device__ __forceinline__ unsigned cvt_pk_bf16(float lo, float hi) { unsigned r; asm volatile("v_cvt_pk_bf16_f32 %0, %1, %2" : "=v"(r) : "v"(lo), "v"(hi)); return r; }
; __device__ __forceinline__ float bflo(unsigned w) { return __uint_as_float(w << 16); }
; __device__ __forceinline__ float bfhi(unsigned w) { return __uint_as_float(w & 0xffff0000u); }
;     __device__ __forceinline__ void operator()(const f32x4 (&acc)[2][2][4][2], const Unit& u, int wr, int wc, int fr, int fq) const {
;     ...
;         for (int ai = 0; ai < 2; ++ai)
; #pragma unroll
;             for (int m = 0; m < 4; ++m) { const size_t r = (size_t)(row0 + ai * HALF + m * 16);
; #pragma unroll
;                 for (int bj = 0; bj < 2; ++bj) { const u32x4 b = *(const u32x4*)(gates + r * 4096 + 2048 + col0 + bj * HALF);
;                     const f32x4 v0 = acc[ai][bj][m][0], v1 = acc[ai][bj][m][1];
;                     u32x4 w; w.x = cvt_pk_bf16(v0[0] * bflo(b[0]), v0[1] * bfhi(b[0])); w.y = cvt_pk_bf16(v0[2] * bflo(b[1]), v0[3] * bfhi(b[1]));
;                     w.z = cvt_pk_bf16(v1[0] * bflo(b[2]), v1[1] * bfhi(b[2])); w.w = cvt_pk_bf16(v1[2] * bflo(b[3]), v1[3] * bfhi(b[3]));
;                     *(u32x4*)(O + r * 2048 + col0 + bj * HALF) = w; }
;                 asm volatile("" ::: "memory"); }
	v_lshlrev_b32_e32 v238, 16, v184
	v_and_b32_e32 v239, 0xffff0000, v184
	v_lshlrev_b32_e32 v184, 16, v185
	v_and_b32_e32 v185, 0xffff0000, v185
	v_lshlrev_b32_e32 v240, 16, v186
	v_and_b32_e32 v241, 0xffff0000, v186
	v_lshlrev_b32_e32 v186, 16, v187
	v_and_b32_e32 v187, 0xffff0000, v187
	v_pk_mul_f32 v[72:73], v[72:73], v[238:239]
	v_pk_mul_f32 v[74:75], v[74:75], v[184:185]
	v_pk_mul_f32 v[76:77], v[76:77], v[240:241]
	v_pk_mul_f32 v[78:79], v[78:79], v[186:187]
	v_cvt_pk_bf16_f32 v72, v72, v73
	v_cvt_pk_bf16_f32 v73, v74, v75
	v_cvt_pk_bf16_f32 v74, v76, v77
	v_cvt_pk_bf16_f32 v75, v78, v79
	global_store_dwordx4 v[154:155], v[72:75], off offset:256
	s_mov_b64 s[0:1], 0x10000
	v_lshl_add_u64 v[154:155], v[154:155], 0, s[0:1]
	s_waitcnt vmcnt(15)
	v_lshlrev_b32_e32 v234, 16, v190
	v_and_b32_e32 v235, 0xffff0000, v190
	v_lshlrev_b32_e32 v190, 16, v191
	v_and_b32_e32 v191, 0xffff0000, v191
	v_lshlrev_b32_e32 v236, 16, v192
	v_and_b32_e32 v237, 0xffff0000, v192
	v_lshlrev_b32_e32 v192, 16, v193
	v_and_b32_e32 v193, 0xffff0000, v193
	v_pk_mul_f32 v[100:101], v[100:101], v[234:235]
	v_pk_mul_f32 v[102:103], v[102:103], v[190:191]
	v_pk_mul_f32 v[96:97], v[96:97], v[236:237]
	v_pk_mul_f32 v[98:99], v[98:99], v[192:193]
	v_cvt_pk_bf16_f32 v100, v100, v101
	v_cvt_pk_bf16_f32 v101, v102, v103
	v_cvt_pk_bf16_f32 v102, v96, v97
	v_cvt_pk_bf16_f32 v103, v98, v99
	global_store_dwordx4 v[154:155], v[100:103], off
	s_waitcnt vmcnt(15)
	v_lshlrev_b32_e32 v238, 16, v194
	v_and_b32_e32 v239, 0xffff0000, v194
	v_lshlrev_b32_e32 v194, 16, v195
	v_and_b32_e32 v195, 0xffff0000, v195
	v_lshlrev_b32_e32 v240, 16, v196
	v_and_b32_e32 v241, 0xffff0000, v196
	v_lshlrev_b32_e32 v196, 16, v197
	v_and_b32_e32 v197, 0xffff0000, v197
	v_pk_mul_f32 v[64:65], v[64:65], v[238:239]
	v_pk_mul_f32 v[66:67], v[66:67], v[194:195]
	v_pk_mul_f32 v[68:69], v[68:69], v[240:241]
	v_pk_mul_f32 v[70:71], v[70:71], v[196:197]
	v_cvt_pk_bf16_f32 v64, v64, v65
	v_cvt_pk_bf16_f32 v65, v66, v67
	v_cvt_pk_bf16_f32 v66, v68, v69
	v_cvt_pk_bf16_f32 v67, v70, v71
	global_store_dwordx4 v[154:155], v[64:67], off offset:256
	s_mov_b64 s[0:1], 0x50000
	v_lshl_add_u64 v[154:155], v[154:155], 0, s[0:1]
	s_waitcnt vmcnt(15)
	v_lshlrev_b32_e32 v234, 16, v198
	v_and_b32_e32 v235, 0xffff0000, v198
	v_lshlrev_b32_e32 v198, 16, v199
	v_and_b32_e32 v199, 0xffff0000, v199
	v_lshlrev_b32_e32 v236, 16, v200
	v_and_b32_e32 v237, 0xffff0000, v200
	v_lshlrev_b32_e32 v200, 16, v201
	v_and_b32_e32 v201, 0xffff0000, v201
	v_pk_mul_f32 v[60:61], v[60:61], v[234:235]
	v_pk_mul_f32 v[62:63], v[62:63], v[198:199]
	v_pk_mul_f32 v[56:57], v[56:57], v[236:237]
	v_pk_mul_f32 v[58:59], v[58:59], v[200:201]
	v_cvt_pk_bf16_f32 v60, v60, v61
	v_cvt_pk_bf16_f32 v61, v62, v63
	v_cvt_pk_bf16_f32 v62, v56, v57
	v_cvt_pk_bf16_f32 v63, v58, v59
	global_store_dwordx4 v[154:155], v[60:63], off
	s_waitcnt vmcnt(15)
	v_lshlrev_b32_e32 v238, 16, v202
	v_and_b32_e32 v239, 0xffff0000, v202
	v_lshlrev_b32_e32 v202, 16, v203
	v_and_b32_e32 v203, 0xffff0000, v203
	v_lshlrev_b32_e32 v240, 16, v204
	v_and_b32_e32 v241, 0xffff0000, v204
	v_lshlrev_b32_e32 v204, 16, v205
	v_and_b32_e32 v205, 0xffff0000, v205
	v_pk_mul_f32 v[52:53], v[52:53], v[238:239]
	v_pk_mul_f32 v[54:55], v[54:55], v[202:203]
	v_pk_mul_f32 v[48:49], v[48:49], v[240:241]
	v_pk_mul_f32 v[50:51], v[50:51], v[204:205]
	v_cvt_pk_bf16_f32 v52, v52, v53
	v_cvt_pk_bf16_f32 v53, v54, v55
	v_cvt_pk_bf16_f32 v54, v48, v49
	v_cvt_pk_bf16_f32 v55, v50, v51
	global_store_dwordx4 v[154:155], v[52:55], off offset:256
	s_mov_b64 s[0:1], 0x10000
	v_lshl_add_u64 v[154:155], v[154:155], 0, s[0:1]
	s_waitcnt vmcnt(15)
	v_lshlrev_b32_e32 v234, 16, v206
	v_and_b32_e32 v235, 0xffff0000, v206
	v_lshlrev_b32_e32 v206, 16, v207
	v_and_b32_e32 v207, 0xffff0000, v207
	v_lshlrev_b32_e32 v236, 16, v208
	v_and_b32_e32 v237, 0xffff0000, v208
	v_lshlrev_b32_e32 v208, 16, v209
	v_and_b32_e32 v209, 0xffff0000, v209
	v_pk_mul_f32 v[44:45], v[44:45], v[234:235]
	v_pk_mul_f32 v[46:47], v[46:47], v[206:207]
	v_pk_mul_f32 v[40:41], v[40:41], v[236:237]
	v_pk_mul_f32 v[42:43], v[42:43], v[208:209]
	v_cvt_pk_bf16_f32 v44, v44, v45
	v_cvt_pk_bf16_f32 v45, v46, v47
	v_cvt_pk_bf16_f32 v46, v40, v41
	v_cvt_pk_bf16_f32 v47, v42, v43
	global_store_dwordx4 v[154:155], v[44:47], off
	s_waitcnt vmcnt(15)
; __device__ __forceinline__ unsigned cvt_pk_bf16(float lo, float hi) { unsigned r; asm volatile("v_cvt_pk_bf16_f32 %0, %1, %2" : "=v"(r) : "v"(lo), "v"(hi)); return r; }
; __device__ __forceinline__ float bflo(unsigned w) { return __uint_as_float(w << 16); }
; __device__ __forceinline__ float bfhi(unsigned w) { return __uint_as_float(w & 0xffff0000u); }
;     __device__ __forceinline__ void operator()(const f32x4 (&acc)[2][2][4][2], const Unit& u, int wr, int wc, int fr, int fq) const {
;     ...
;         for (int ai = 0; ai < 2; ++ai)
; #pragma unroll
;             for (int m = 0; m < 4; ++m) { const size_t r = (size_t)(row0 + ai * HALF + m * 16);
; #pragma unroll
;                 for (int bj = 0; bj < 2; ++bj) { const u32x4 b = *(const u32x4*)(gates + r * 4096 + 2048 + col0 + bj * HALF);
;                     const f32x4 v0 = acc[ai][bj][m][0], v1 = acc[ai][bj][m][1];
;                     u32x4 w; w.x = cvt_pk_bf16(v0[0] * bflo(b[0]), v0[1] * bfhi(b[0])); w.y = cvt_pk_bf16(v0[2] * bflo(b[1]), v0[3] * bfhi(b[1]));
;                     w.z = cvt_pk_bf16(v1[0] * bflo(b[2]), v1[1] * bfhi(b[2])); w.w = cvt_pk_bf16(v1[2] * bflo(b[3]), v1[3] * bfhi(b[3]));
;                     *(u32x4*)(O + r * 2048 + col0 + bj * HALF) = w; }
;                 asm volatile("" ::: "memory"); }
;     }
	v_lshlrev_b32_e32 v238, 16, v214
	v_and_b32_e32 v239, 0xffff0000, v214
	v_lshlrev_b32_e32 v214, 16, v215
	v_and_b32_e32 v215, 0xffff0000, v215
	v_lshlrev_b32_e32 v240, 16, v216
	v_and_b32_e32 v241, 0xffff0000, v216
	v_lshlrev_b32_e32 v216, 16, v217
	v_and_b32_e32 v217, 0xffff0000, v217
	v_pk_mul_f32 v[36:37], v[36:37], v[238:239]
	v_pk_mul_f32 v[38:39], v[38:39], v[214:215]
	v_pk_mul_f32 v[32:33], v[32:33], v[240:241]
	v_pk_mul_f32 v[34:35], v[34:35], v[216:217]
	v_cvt_pk_bf16_f32 v36, v36, v37
	v_cvt_pk_bf16_f32 v37, v38, v39
	v_cvt_pk_bf16_f32 v38, v32, v33
	v_cvt_pk_bf16_f32 v39, v34, v35
	global_store_dwordx4 v[154:155], v[36:39], off offset:256
	s_mov_b64 s[0:1], 0x10000
	v_lshl_add_u64 v[154:155], v[154:155], 0, s[0:1]
	s_waitcnt vmcnt(15)
	v_lshlrev_b32_e32 v234, 16, v218
	v_and_b32_e32 v235, 0xffff0000, v218
	v_lshlrev_b32_e32 v218, 16, v219
	v_and_b32_e32 v219, 0xffff0000, v219
	v_lshlrev_b32_e32 v236, 16, v220
	v_and_b32_e32 v237, 0xffff0000, v220
	v_lshlrev_b32_e32 v220, 16, v221
	v_and_b32_e32 v221, 0xffff0000, v221
	v_pk_mul_f32 v[28:29], v[28:29], v[234:235]
	v_pk_mul_f32 v[30:31], v[30:31], v[218:219]
	v_pk_mul_f32 v[24:25], v[24:25], v[236:237]
	v_pk_mul_f32 v[26:27], v[26:27], v[220:221]
	v_cvt_pk_bf16_f32 v28, v28, v29
	v_cvt_pk_bf16_f32 v29, v30, v31
	v_cvt_pk_bf16_f32 v30, v24, v25
	v_cvt_pk_bf16_f32 v31, v26, v27
	global_store_dwordx4 v[154:155], v[28:31], off
	s_waitcnt vmcnt(15)
	v_lshlrev_b32_e32 v238, 16, v222
	v_and_b32_e32 v239, 0xffff0000, v222
	v_lshlrev_b32_e32 v222, 16, v223
	v_and_b32_e32 v223, 0xffff0000, v223
	v_lshlrev_b32_e32 v240, 16, v224
	v_and_b32_e32 v241, 0xffff0000, v224
	v_lshlrev_b32_e32 v224, 16, v225
	v_and_b32_e32 v225, 0xffff0000, v225
	v_pk_mul_f32 v[20:21], v[20:21], v[238:239]
	v_pk_mul_f32 v[22:23], v[22:23], v[222:223]
	v_pk_mul_f32 v[16:17], v[16:17], v[240:241]
	v_pk_mul_f32 v[18:19], v[18:19], v[224:225]
	v_cvt_pk_bf16_f32 v20, v20, v21
	v_cvt_pk_bf16_f32 v21, v22, v23
	v_cvt_pk_bf16_f32 v22, v16, v17
	v_cvt_pk_bf16_f32 v23, v18, v19
	global_store_dwordx4 v[154:155], v[20:23], off offset:256
	s_mov_b64 s[0:1], 0x10000
	v_lshl_add_u64 v[154:155], v[154:155], 0, s[0:1]
	s_waitcnt vmcnt(15)
	v_lshlrev_b32_e32 v234, 16, v226
	v_and_b32_e32 v235, 0xffff0000, v226
	v_lshlrev_b32_e32 v226, 16, v227
	v_and_b32_e32 v227, 0xffff0000, v227
	v_lshlrev_b32_e32 v236, 16, v228
	v_and_b32_e32 v237, 0xffff0000, v228
	v_lshlrev_b32_e32 v228, 16, v229
	v_and_b32_e32 v229, 0xffff0000, v229
	v_pk_mul_f32 v[12:13], v[12:13], v[234:235]
	v_pk_mul_f32 v[14:15], v[14:15], v[226:227]
	v_pk_mul_f32 v[8:9], v[8:9], v[236:237]
	v_pk_mul_f32 v[10:11], v[10:11], v[228:229]
	v_cvt_pk_bf16_f32 v12, v12, v13
	v_cvt_pk_bf16_f32 v13, v14, v15
	v_cvt_pk_bf16_f32 v14, v8, v9
	v_cvt_pk_bf16_f32 v15, v10, v11
	global_store_dwordx4 v[154:155], v[12:15], off
	s_waitcnt vmcnt(15)
	v_lshlrev_b32_e32 v238, 16, v230
	v_and_b32_e32 v239, 0xffff0000, v230
	v_lshlrev_b32_e32 v230, 16, v231
	v_and_b32_e32 v231, 0xffff0000, v231
	v_lshlrev_b32_e32 v240, 16, v232
	v_and_b32_e32 v241, 0xffff0000, v232
	v_lshlrev_b32_e32 v232, 16, v233
	v_and_b32_e32 v233, 0xffff0000, v233
	v_pk_mul_f32 v[4:5], v[4:5], v[238:239]
	v_pk_mul_f32 v[6:7], v[6:7], v[230:231]
	v_pk_mul_f32 v[0:1], v[0:1], v[240:241]
	v_pk_mul_f32 v[2:3], v[2:3], v[232:233]
	v_cvt_pk_bf16_f32 v4, v4, v5
	v_cvt_pk_bf16_f32 v5, v6, v7
	v_cvt_pk_bf16_f32 v6, v0, v1
	v_cvt_pk_bf16_f32 v7, v2, v3
	global_store_dwordx4 v[154:155], v[4:7], off offset:256
	s_mov_b64 s[0:1], -1
	s_andn2_b64 vcc, exec, s[2:3]
	s_cbranch_vccnz .LBB0_695
	s_andn2_b64 vcc, exec, s[6:7]
	s_cbranch_vccnz .LBB0_694
	s_barrier
	s_branch .LBB0_694

; __device__ __forceinline__ unsigned cvt_pk_bf16(float lo, float hi) { unsigned r; asm volatile("v_cvt_pk_bf16_f32 %0, %1, %2" : "=v"(r) : "v"(lo), "v"(hi)); return r; }
; __device__ __forceinline__ float bflo(unsigned w) { return __uint_as_float(w << 16); }
; __device__ __forceinline__ float bfhi(unsigned w) { return __uint_as_float(w & 0xffff0000u); }
;     __device__ __forceinline__ void operator()(const f32x4 (&acc)[2][2][4][2], const Unit& u, int wr, int wc, int fr, int fq) const {
;         const int row0 = u.pm * BM + wr * 64 + fr, col0 = u.pn * BM + wc * 32 + 8 * fq;
;         const float* gb = g + (size_t)(u.pm >> 3) * 12288 + col0;
;         f32x4 gv[2][2];
; #pragma unroll
;         for (int bj = 0; bj < 2; ++bj)
; #pragma unroll
;             for (int n = 0; n < 2; ++n) gv[bj][n] = *(const f32x4*)(gb + bj * HALF + n * 4);
; #pragma unroll
;         for (int ai = 0; ai < 2; ++ai)
; #pragma unroll
;             for (int m = 0; m < 4; ++m) { const size_t off = (size_t)(row0 + ai * HALF + m * 16) * 2048 + col0;
; #pragma unroll
;                 for (int bj = 0; bj < 2; ++bj) { f32x4 b0, b1;
;                     if constexpr (sizeof(TB) == 4) { b0 = __builtin_nontemporal_load((const f32x4*)((const float*)base + off + bj * HALF)); b1 = __builtin_nontemporal_load((const f32x4*)((const float*)base + off + bj * HALF + 4)); }
;                     else { const u32x4 t = *(const u32x4*)((const bf16_t*)base + off + bj * HALF);
;                         b0[0] = bflo(t[0]); b0[1] = bfhi(t[0]); b0[2] = bflo(t[1]); b0[3] = bfhi(t[1]); b1[0] = bflo(t[2]); b1[1] = bfhi(t[2]); b1[2] = bflo(t[3]); b1[3] = bfhi(t[3]); }
;                     const f32x4 v0 = b0 + gv[bj][0] * acc[ai][bj][m][0], v1 = b1 + gv[bj][1] * acc[ai][bj][m][1];
;                     u32x4 w; w.x = cvt_pk_bf16(v0[0], v0[1]); w.y = cvt_pk_bf16(v0[2], v0[3]); w.z = cvt_pk_bf16(v1[0], v1[1]); w.w = cvt_pk_bf16(v1[2], v1[3]);
;                     *(u32x4*)(out + off + bj * HALF) = w; } }
.LBB0_784:
	v_lshl_add_u32 v164, s60, 8, v166
	v_lshl_or_b32 v162, s70, 8, v168
	s_ashr_i32 s0, s60, 3
	v_ashrrev_i32_e32 v165, 31, v164
	s_mul_hi_i32 s1, s0, 0xc000
	s_mul_i32 s0, s0, 0xc000
	v_ashrrev_i32_e32 v163, 31, v162
	v_lshlrev_b64 v[128:129], 11, v[164:165]
	s_add_u32 s0, s33, s0
	v_lshl_add_u64 v[160:161], v[128:129], 0, v[162:163]
	s_addc_u32 s1, s61, s1
	v_lshl_add_u64 v[180:181], v[160:161], 2, s[52:53]
	v_lshl_add_u64 v[132:133], v[162:163], 2, s[0:1]
	v_lshl_add_u64 v[182:183], v[160:161], 1, s[72:73]
	global_load_dwordx4 v[172:175], v[180:181], off nt
	global_load_dwordx4 v[176:179], v[180:181], off offset:16 nt
	global_load_dwordx4 v[184:187], v[180:181], off offset:512 nt
	global_load_dwordx4 v[160:163], v[180:181], off offset:528 nt
	s_mov_b64 s[0:1], 0x20000
	v_lshl_add_u64 v[180:181], v[180:181], 0, s[0:1]
	global_load_dwordx4 v[140:143], v[132:133], off
	global_load_dwordx4 v[136:139], v[132:133], off offset:16
	global_load_dwordx4 v[128:131], v[132:133], off offset:528
	global_load_dwordx4 v[132:135], v[132:133], off offset:512
	global_load_dwordx4 v[190:193], v[180:181], off nt
	global_load_dwordx4 v[194:197], v[180:181], off offset:16 nt
	global_load_dwordx4 v[198:201], v[180:181], off offset:512 nt
	global_load_dwordx4 v[202:205], v[180:181], off offset:528 nt
	s_mov_b64 s[0:1], 0x20000
	v_lshl_add_u64 v[180:181], v[180:181], 0, s[0:1]
	global_load_dwordx4 v[206:209], v[180:181], off nt
	global_load_dwordx4 v[214:217], v[180:181], off offset:16 nt
	global_load_dwordx4 v[218:221], v[180:181], off offset:512 nt
	global_load_dwordx4 v[222:225], v[180:181], off offset:528 nt
	s_mov_b64 s[0:1], 0x20000
	v_lshl_add_u64 v[180:181], v[180:181], 0, s[0:1]
	global_load_dwordx4 v[226:229], v[180:181], off nt
	global_load_dwordx4 v[230:233], v[180:181], off offset:16 nt
	global_load_dwordx4 v[234:237], v[180:181], off offset:512 nt
	global_load_dwordx4 v[238:241], v[180:181], off offset:528 nt
	s_mov_b64 s[0:1], 0xa0000
	v_lshl_add_u64 v[180:181], v[180:181], 0, s[0:1]
	s_waitcnt vmcnt(12)
	s_waitcnt vmcnt(18)
	v_pk_fma_f32 v[124:125], v[124:125], v[140:141], v[172:173]
	v_pk_fma_f32 v[126:127], v[126:127], v[142:143], v[174:175]
	v_pk_fma_f32 v[120:121], v[120:121], v[136:137], v[176:177]
	v_pk_fma_f32 v[122:123], v[122:123], v[138:139], v[178:179]
	v_cvt_pk_bf16_f32 v124, v124, v125
	v_cvt_pk_bf16_f32 v125, v126, v127
	v_cvt_pk_bf16_f32 v126, v120, v121
	v_cvt_pk_bf16_f32 v127, v122, v123
	global_store_dwordx4 v[182:183], v[124:127], off
	s_waitcnt vmcnt(17)
	v_pk_fma_f32 v[116:117], v[116:117], v[132:133], v[184:185]
	v_pk_fma_f32 v[118:119], v[118:119], v[134:135], v[186:187]
	v_pk_fma_f32 v[112:113], v[112:113], v[128:129], v[160:161]
	v_pk_fma_f32 v[114:115], v[114:115], v[130:131], v[162:163]
	v_cvt_pk_bf16_f32 v116, v116, v117
	v_cvt_pk_bf16_f32 v117, v118, v119
	v_cvt_pk_bf16_f32 v118, v112, v113
	v_cvt_pk_bf16_f32 v119, v114, v115
	global_store_dwordx4 v[182:183], v[116:119], off offset:256
	s_mov_b64 s[0:1], 0x10000
	v_lshl_add_u64 v[182:183], v[182:183], 0, s[0:1]
	global_load_dwordx4 v[172:175], v[180:181], off nt
	global_load_dwordx4 v[176:179], v[180:181], off offset:16 nt
	global_load_dwordx4 v[184:187], v[180:181], off offset:512 nt
	global_load_dwordx4 v[160:163], v[180:181], off offset:528 nt
	s_mov_b64 s[0:1], 0x20000
	v_lshl_add_u64 v[180:181], v[180:181], 0, s[0:1]
	s_waitcnt vmcnt(16)
	v_pk_fma_f32 v[108:109], v[108:109], v[140:141], v[190:191]
	v_pk_fma_f32 v[110:111], v[110:111], v[142:143], v[192:193]
	v_pk_fma_f32 v[104:105], v[104:105], v[136:137], v[194:195]
	v_pk_fma_f32 v[106:107], v[106:107], v[138:139], v[196:197]
	v_cvt_pk_bf16_f32 v108, v108, v109
	v_cvt_pk_bf16_f32 v109, v110, v111
	v_cvt_pk_bf16_f32 v110, v104, v105
	v_cvt_pk_bf16_f32 v111, v106, v107
	global_store_dwordx4 v[182:183], v[108:111], off
	s_waitcnt vmcnt(15)
	v_pk_fma_f32 v[100:101], v[100:101], v[132:133], v[198:199]
	v_pk_fma_f32 v[102:103], v[102:103], v[134:135], v[200:201]
	v_pk_fma_f32 v[96:97], v[96:97], v[128:129], v[202:203]
	v_pk_fma_f32 v[98:99], v[98:99], v[130:131], v[204:205]
	v_cvt_pk_bf16_f32 v100, v100, v101
	v_cvt_pk_bf16_f32 v101, v102, v103
	v_cvt_pk_bf16_f32 v102, v96, v97
	v_cvt_pk_bf16_f32 v103, v98, v99
	global_store_dwordx4 v[182:183], v[100:103], off offset:256
	s_mov_b64 s[0:1], 0x10000
	v_lshl_add_u64 v[182:183], v[182:183], 0, s[0:1]
	global_load_dwordx4 v[190:193], v[180:181], off nt
	global_load_dwordx4 v[194:197], v[180:181], off offset:16 nt
	global_load_dwordx4 v[198:201], v[180:181], off offset:512 nt
	global_load_dwordx4 v[202:205], v[180:181], off offset:528 nt
	s_mov_b64 s[0:1], 0x20000
	v_lshl_add_u64 v[180:181], v[180:181], 0, s[0:1]
	s_waitcnt vmcnt(18)
	v_pk_fma_f32 v[92:93], v[92:93], v[140:141], v[206:207]
	v_pk_fma_f32 v[94:95], v[94:95], v[142:143], v[208:209]
	v_pk_fma_f32 v[88:89], v[88:89], v[136:137], v[214:215]
	v_pk_fma_f32 v[90:91], v[90:91], v[138:139], v[216:217]
	v_cvt_pk_bf16_f32 v92, v92, v93
	v_cvt_pk_bf16_f32 v93, v94, v95
	v_cvt_pk_bf16_f32 v94, v88, v89
	v_cvt_pk_bf16_f32 v95, v90, v91
	global_store_dwordx4 v[182:183], v[92:95], off
	s_waitcnt vmcnt(17)
; __device__ __forceinline__ unsigned cvt_pk_bf16(float lo, float hi) { unsigned r; asm volatile("v_cvt_pk_bf16_f32 %0, %1, %2" : "=v"(r) : "v"(lo), "v"(hi)); return r; }
; __device__ __forceinline__ float bflo(unsigned w) { return __uint_as_float(w << 16); }
; __device__ __forceinline__ float bfhi(unsigned w) { return __uint_as_float(w & 0xffff0000u); }
;     __device__ __forceinline__ void operator()(const f32x4 (&acc)[2][2][4][2], const Unit& u, int wr, int wc, int fr, int fq) const {
;     ...
; #pragma unroll
;         for (int ai = 0; ai < 2; ++ai)
; #pragma unroll
;             for (int m = 0; m < 4; ++m) { const size_t off = (size_t)(row0 + ai * HALF + m * 16) * 2048 + col0;
; #pragma unroll
;                 for (int bj = 0; bj < 2; ++bj) { f32x4 b0, b1;
;                     if constexpr (sizeof(TB) == 4) { b0 = __builtin_nontemporal_load((const f32x4*)((const float*)base + off + bj * HALF)); b1 = __builtin_nontemporal_load((const f32x4*)((const float*)base + off + bj * HALF + 4)); }
;                     else { const u32x4 t = *(const u32x4*)((const bf16_t*)base + off + bj * HALF);
;                         b0[0] = bflo(t[0]); b0[1] = bfhi(t[0]); b0[2] = bflo(t[1]); b0[3] = bfhi(t[1]); b1[0] = bflo(t[2]); b1[1] = bfhi(t[2]); b1[2] = bflo(t[3]); b1[3] = bfhi(t[3]); }
;                     const f32x4 v0 = b0 + gv[bj][0] * acc[ai][bj][m][0], v1 = b1 + gv[bj][1] * acc[ai][bj][m][1];
;                     u32x4 w; w.x = cvt_pk_bf16(v0[0], v0[1]); w.y = cvt_pk_bf16(v0[2], v0[3]); w.z = cvt_pk_bf16(v1[0], v1[1]); w.w = cvt_pk_bf16(v1[2], v1[3]);
;                     *(u32x4*)(out + off + bj * HALF) = w; } }
	v_pk_fma_f32 v[84:85], v[84:85], v[132:133], v[218:219]
	v_pk_fma_f32 v[86:87], v[86:87], v[134:135], v[220:221]
	v_pk_fma_f32 v[80:81], v[80:81], v[128:129], v[222:223]
	v_pk_fma_f32 v[82:83], v[82:83], v[130:131], v[224:225]
	v_cvt_pk_bf16_f32 v84, v84, v85
	v_cvt_pk_bf16_f32 v85, v86, v87
	v_cvt_pk_bf16_f32 v86, v80, v81
	v_cvt_pk_bf16_f32 v87, v82, v83
	global_store_dwordx4 v[182:183], v[84:87], off offset:256
	s_mov_b64 s[0:1], 0x10000
	v_lshl_add_u64 v[182:183], v[182:183], 0, s[0:1]
	global_load_dwordx4 v[206:209], v[180:181], off nt
	global_load_dwordx4 v[214:217], v[180:181], off offset:16 nt
	global_load_dwordx4 v[218:221], v[180:181], off offset:512 nt
	global_load_dwordx4 v[222:225], v[180:181], off offset:528 nt
	s_mov_b64 s[0:1], 0x20000
	v_lshl_add_u64 v[180:181], v[180:181], 0, s[0:1]
	s_waitcnt vmcnt(20)
	v_pk_fma_f32 v[76:77], v[76:77], v[140:141], v[226:227]
	v_pk_fma_f32 v[78:79], v[78:79], v[142:143], v[228:229]
	v_pk_fma_f32 v[72:73], v[72:73], v[136:137], v[230:231]
	v_pk_fma_f32 v[74:75], v[74:75], v[138:139], v[232:233]
	v_cvt_pk_bf16_f32 v76, v76, v77
	v_cvt_pk_bf16_f32 v77, v78, v79
	v_cvt_pk_bf16_f32 v78, v72, v73
	v_cvt_pk_bf16_f32 v79, v74, v75
	global_store_dwordx4 v[182:183], v[76:79], off
	s_waitcnt vmcnt(19)
	v_pk_fma_f32 v[68:69], v[68:69], v[132:133], v[234:235]
	v_pk_fma_f32 v[70:71], v[70:71], v[134:135], v[236:237]
	v_pk_fma_f32 v[64:65], v[64:65], v[128:129], v[238:239]
	v_pk_fma_f32 v[66:67], v[66:67], v[130:131], v[240:241]
	v_cvt_pk_bf16_f32 v68, v68, v69
	v_cvt_pk_bf16_f32 v69, v70, v71
	v_cvt_pk_bf16_f32 v70, v64, v65
	v_cvt_pk_bf16_f32 v71, v66, v67
	global_store_dwordx4 v[182:183], v[68:71], off offset:256
	s_mov_b64 s[0:1], 0x50000
	v_lshl_add_u64 v[182:183], v[182:183], 0, s[0:1]
	global_load_dwordx4 v[226:229], v[180:181], off nt
	global_load_dwordx4 v[230:233], v[180:181], off offset:16 nt
	global_load_dwordx4 v[234:237], v[180:181], off offset:512 nt
	global_load_dwordx4 v[238:241], v[180:181], off offset:528 nt
	s_waitcnt vmcnt(20)
	v_pk_fma_f32 v[60:61], v[60:61], v[140:141], v[172:173]
	v_pk_fma_f32 v[62:63], v[62:63], v[142:143], v[174:175]
	v_pk_fma_f32 v[56:57], v[56:57], v[136:137], v[176:177]
	v_pk_fma_f32 v[58:59], v[58:59], v[138:139], v[178:179]
	v_cvt_pk_bf16_f32 v60, v60, v61
	v_cvt_pk_bf16_f32 v61, v62, v63
	v_cvt_pk_bf16_f32 v62, v56, v57
	v_cvt_pk_bf16_f32 v63, v58, v59
	global_store_dwordx4 v[182:183], v[60:63], off
	s_waitcnt vmcnt(19)
	v_pk_fma_f32 v[52:53], v[52:53], v[132:133], v[184:185]
	v_pk_fma_f32 v[54:55], v[54:55], v[134:135], v[186:187]
	v_pk_fma_f32 v[48:49], v[48:49], v[128:129], v[160:161]
	v_pk_fma_f32 v[50:51], v[50:51], v[130:131], v[162:163]
	v_cvt_pk_bf16_f32 v52, v52, v53
	v_cvt_pk_bf16_f32 v53, v54, v55
	v_cvt_pk_bf16_f32 v54, v48, v49
	v_cvt_pk_bf16_f32 v55, v50, v51
	global_store_dwordx4 v[182:183], v[52:55], off offset:256
	s_mov_b64 s[0:1], 0x10000
	v_lshl_add_u64 v[182:183], v[182:183], 0, s[0:1]
	s_waitcnt vmcnt(16)
	v_pk_fma_f32 v[44:45], v[44:45], v[140:141], v[190:191]
	v_pk_fma_f32 v[46:47], v[46:47], v[142:143], v[192:193]
	v_pk_fma_f32 v[40:41], v[40:41], v[136:137], v[194:195]
	v_pk_fma_f32 v[42:43], v[42:43], v[138:139], v[196:197]
	v_cvt_pk_bf16_f32 v44, v44, v45
	v_cvt_pk_bf16_f32 v45, v46, v47
	v_cvt_pk_bf16_f32 v46, v40, v41
	v_cvt_pk_bf16_f32 v47, v42, v43
	global_store_dwordx4 v[182:183], v[44:47], off
	s_waitcnt vmcnt(15)
	v_pk_fma_f32 v[36:37], v[36:37], v[132:133], v[198:199]
	v_pk_fma_f32 v[38:39], v[38:39], v[134:135], v[200:201]
	v_pk_fma_f32 v[32:33], v[32:33], v[128:129], v[202:203]
	v_pk_fma_f32 v[34:35], v[34:35], v[130:131], v[204:205]
	v_cvt_pk_bf16_f32 v36, v36, v37
	v_cvt_pk_bf16_f32 v37, v38, v39
	v_cvt_pk_bf16_f32 v38, v32, v33
	v_cvt_pk_bf16_f32 v39, v34, v35
	global_store_dwordx4 v[182:183], v[36:39], off offset:256
	s_mov_b64 s[0:1], 0x10000
	v_lshl_add_u64 v[182:183], v[182:183], 0, s[0:1]
	s_waitcnt vmcnt(12)
	v_pk_fma_f32 v[28:29], v[28:29], v[140:141], v[206:207]
	v_pk_fma_f32 v[30:31], v[30:31], v[142:143], v[208:209]
	v_pk_fma_f32 v[24:25], v[24:25], v[136:137], v[214:215]
	v_pk_fma_f32 v[26:27], v[26:27], v[138:139], v[216:217]
	v_cvt_pk_bf16_f32 v28, v28, v29
	v_cvt_pk_bf16_f32 v29, v30, v31
	v_cvt_pk_bf16_f32 v30, v24, v25
	v_cvt_pk_bf16_f32 v31, v26, v27
	global_store_dwordx4 v[182:183], v[28:31], off
	s_waitcnt vmcnt(11)
	v_pk_fma_f32 v[20:21], v[20:21], v[132:133], v[218:219]
	v_pk_fma_f32 v[22:23], v[22:23], v[134:135], v[220:221]
	v_pk_fma_f32 v[16:17], v[16:17], v[128:129], v[222:223]
	v_pk_fma_f32 v[18:19], v[18:19], v[130:131], v[224:225]
	v_cvt_pk_bf16_f32 v20, v20, v21
	v_cvt_pk_bf16_f32 v21, v22, v23
	v_cvt_pk_bf16_f32 v22, v16, v17
	v_cvt_pk_bf16_f32 v23, v18, v19
	global_store_dwordx4 v[182:183], v[20:23], off offset:256
	s_mov_b64 s[0:1], 0x10000
	v_lshl_add_u64 v[182:183], v[182:183], 0, s[0:1]
	s_waitcnt vmcnt(8)
	v_pk_fma_f32 v[12:13], v[12:13], v[140:141], v[226:227]
	v_pk_fma_f32 v[14:15], v[14:15], v[142:143], v[228:229]
	v_pk_fma_f32 v[8:9], v[8:9], v[136:137], v[230:231]
	v_pk_fma_f32 v[10:11], v[10:11], v[138:139], v[232:233]
	v_cvt_pk_bf16_f32 v12, v12, v13
	v_cvt_pk_bf16_f32 v13, v14, v15
	v_cvt_pk_bf16_f32 v14, v8, v9
	v_cvt_pk_bf16_f32 v15, v10, v11
	global_store_dwordx4 v[182:183], v[12:15], off
	s_waitcnt vmcnt(7)
	v_pk_fma_f32 v[4:5], v[4:5], v[132:133], v[234:235]
	v_pk_fma_f32 v[6:7], v[6:7], v[134:135], v[236:237]
	v_pk_fma_f32 v[0:1], v[0:1], v[128:129], v[238:239]
	v_pk_fma_f32 v[2:3], v[2:3], v[130:131], v[240:241]
	v_cvt_pk_bf16_f32 v4, v4, v5
	v_cvt_pk_bf16_f32 v5, v6, v7
	v_cvt_pk_bf16_f32 v6, v0, v1
	v_cvt_pk_bf16_f32 v7, v2, v3
	global_store_dwordx4 v[182:183], v[4:7], off offset:256
	s_andn2_b64 vcc, exec, s[4:5]
	s_mov_b64 s[0:1], -1
	s_cbranch_vccnz .LBB0_773
	s_andn2_b64 vcc, exec, s[6:7]
	s_cbranch_vccnz .LBB0_772
	s_barrier
	s_branch .LBB0_772

; __device__ __forceinline__ unsigned cvt_pk_bf16(float lo, float hi) { unsigned r; asm volatile("v_cvt_pk_bf16_f32 %0, %1, %2" : "=v"(r) : "v"(lo), "v"(hi)); return r; }
; __device__ __forceinline__ float bflo(unsigned w) { return __uint_as_float(w << 16); }
; __device__ __forceinline__ float bfhi(unsigned w) { return __uint_as_float(w & 0xffff0000u); }
;     __device__ __forceinline__ void operator()(const f32x4 (&acc)[2][2][4][2], const Unit& u, int wr, int wc, int fr, int fq) const {
;         const int row0 = u.pm * BM + wr * 64 + fr, col0 = u.pn * BM + wc * 32 + 8 * fq;
;         const float* gb = g + (size_t)(u.pm >> 3) * 12288 + col0;
;         f32x4 gv[2][2];
; #pragma unroll
;         for (int bj = 0; bj < 2; ++bj)
; #pragma unroll
;             for (int n = 0; n < 2; ++n) gv[bj][n] = *(const f32x4*)(gb + bj * HALF + n * 4);
; #pragma unroll
;         for (int ai = 0; ai < 2; ++ai)
; #pragma unroll
;             for (int m = 0; m < 4; ++m) { const size_t off = (size_t)(row0 + ai * HALF + m * 16) * 2048 + col0;
; #pragma unroll
;                 for (int bj = 0; bj < 2; ++bj) { f32x4 b0, b1;
;                     if constexpr (sizeof(TB) == 4) { b0 = __builtin_nontemporal_load((const f32x4*)((const float*)base + off + bj * HALF)); b1 = __builtin_nontemporal_load((const f32x4*)((const float*)base + off + bj * HALF + 4)); }
;                     else { const u32x4 t = *(const u32x4*)((const bf16_t*)base + off + bj * HALF);
;                         b0[0] = bflo(t[0]); b0[1] = bfhi(t[0]); b0[2] = bflo(t[1]); b0[3] = bfhi(t[1]); b1[0] = bflo(t[2]); b1[1] = bfhi(t[2]); b1[2] = bflo(t[3]); b1[3] = bfhi(t[3]); }
;                     const f32x4 v0 = b0 + gv[bj][0] * acc[ai][bj][m][0], v1 = b1 + gv[bj][1] * acc[ai][bj][m][1];
;                     u32x4 w; w.x = cvt_pk_bf16(v0[0], v0[1]); w.y = cvt_pk_bf16(v0[2], v0[3]); w.z = cvt_pk_bf16(v1[0], v1[1]); w.w = cvt_pk_bf16(v1[2], v1[3]);
;                     *(u32x4*)(out + off + bj * HALF) = w; } }
.LBB0_1104:
	v_lshl_add_u32 v164, s57, 8, v166
	v_lshl_or_b32 v162, s58, 8, v168
	v_ashrrev_i32_e32 v165, 31, v164
	v_ashrrev_i32_e32 v163, 31, v162
	v_lshlrev_b64 v[120:121], 11, v[164:165]
	v_lshl_add_u64 v[120:121], v[120:121], 0, v[162:163]
	v_lshlrev_b64 v[160:161], 1, v[120:121]
	s_ashr_i32 s0, s57, 3
	s_mul_hi_i32 s1, s0, 0xc000
	s_mul_i32 s0, s0, 0xc000
	s_add_u32 s0, s45, s0
	s_addc_u32 s1, s46, s1
	v_lshl_add_u64 v[124:125], v[162:163], 2, s[0:1]
	v_lshl_add_u64 v[162:163], s[54:55], 0, v[160:161]
	v_lshl_add_u64 v[160:161], s[72:73], 0, v[160:161]
	s_mov_b64 s[0:1], 0x10000
	global_load_dwordx4 v[172:175], v[160:161], off
	global_load_dwordx4 v[176:179], v[160:161], off offset:256
	v_lshl_add_u64 v[160:161], v[160:161], 0, s[0:1]
	global_load_dwordx4 v[132:135], v[124:125], off
	global_load_dwordx4 v[128:131], v[124:125], off offset:16
	global_load_dwordx4 v[120:123], v[124:125], off offset:528
	global_load_dwordx4 v[124:127], v[124:125], off offset:512
	global_load_dwordx4 v[180:183], v[160:161], off
	global_load_dwordx4 v[184:187], v[160:161], off offset:256
	v_lshl_add_u64 v[160:161], v[160:161], 0, s[0:1]
	global_load_dwordx4 v[190:193], v[160:161], off
	global_load_dwordx4 v[194:197], v[160:161], off offset:256
	v_lshl_add_u64 v[160:161], v[160:161], 0, s[0:1]
	global_load_dwordx4 v[198:201], v[160:161], off
	global_load_dwordx4 v[202:205], v[160:161], off offset:256
	s_mov_b64 s[0:1], 0x50000
	v_lshl_add_u64 v[160:161], v[160:161], 0, s[0:1]
	s_mov_b64 s[0:1], 0x10000
	global_load_dwordx4 v[206:209], v[160:161], off
	global_load_dwordx4 v[214:217], v[160:161], off offset:256
	v_lshl_add_u64 v[160:161], v[160:161], 0, s[0:1]
	global_load_dwordx4 v[218:221], v[160:161], off
	global_load_dwordx4 v[222:225], v[160:161], off offset:256
	v_lshl_add_u64 v[160:161], v[160:161], 0, s[0:1]
	global_load_dwordx4 v[226:229], v[160:161], off
	global_load_dwordx4 v[230:233], v[160:161], off offset:256
	v_lshl_add_u64 v[160:161], v[160:161], 0, s[0:1]
	global_load_dwordx4 v[234:237], v[160:161], off
	global_load_dwordx4 v[238:241], v[160:161], off offset:256
	s_waitcnt vmcnt(14)
	s_waitcnt vmcnt(19)
	v_lshlrev_b32_e32 v164, 16, v172
	v_and_b32_e32 v165, 0xffff0000, v172
	v_lshlrev_b32_e32 v172, 16, v173
	v_and_b32_e32 v173, 0xffff0000, v173
	v_lshlrev_b32_e32 v210, 16, v174
	v_and_b32_e32 v211, 0xffff0000, v174
	v_lshlrev_b32_e32 v174, 16, v175
	v_and_b32_e32 v175, 0xffff0000, v175
	v_pk_fma_f32 v[140:141], v[140:141], v[132:133], v[164:165]
	v_pk_fma_f32 v[142:143], v[142:143], v[134:135], v[172:173]
	v_pk_fma_f32 v[136:137], v[136:137], v[128:129], v[210:211]
	v_pk_fma_f32 v[138:139], v[138:139], v[130:131], v[174:175]
	v_cvt_pk_bf16_f32 v140, v140, v141
	v_cvt_pk_bf16_f32 v141, v142, v143
	v_cvt_pk_bf16_f32 v142, v136, v137
	v_cvt_pk_bf16_f32 v143, v138, v139
	global_store_dwordx4 v[162:163], v[140:143], off
	s_waitcnt vmcnt(19)
	v_lshlrev_b32_e32 v164, 16, v176
	v_and_b32_e32 v165, 0xffff0000, v176
	v_lshlrev_b32_e32 v176, 16, v177
	v_and_b32_e32 v177, 0xffff0000, v177
	v_lshlrev_b32_e32 v210, 16, v178
	v_and_b32_e32 v211, 0xffff0000, v178
	v_lshlrev_b32_e32 v178, 16, v179
	v_and_b32_e32 v179, 0xffff0000, v179
	v_pk_fma_f32 v[112:113], v[112:113], v[124:125], v[164:165]
	v_pk_fma_f32 v[114:115], v[114:115], v[126:127], v[176:177]
	v_pk_fma_f32 v[108:109], v[108:109], v[120:121], v[210:211]
	v_pk_fma_f32 v[110:111], v[110:111], v[122:123], v[178:179]
	v_cvt_pk_bf16_f32 v112, v112, v113
	v_cvt_pk_bf16_f32 v113, v114, v115
	v_cvt_pk_bf16_f32 v114, v108, v109
	v_cvt_pk_bf16_f32 v115, v110, v111
	global_store_dwordx4 v[162:163], v[112:115], off offset:256
	s_mov_b64 s[0:1], 0x10000
	v_lshl_add_u64 v[162:163], v[162:163], 0, s[0:1]
	s_waitcnt vmcnt(15)
	v_lshlrev_b32_e32 v164, 16, v180
	v_and_b32_e32 v165, 0xffff0000, v180
	v_lshlrev_b32_e32 v180, 16, v181
	v_and_b32_e32 v181, 0xffff0000, v181
	v_lshlrev_b32_e32 v210, 16, v182
	v_and_b32_e32 v211, 0xffff0000, v182
	v_lshlrev_b32_e32 v182, 16, v183
	v_and_b32_e32 v183, 0xffff0000, v183
	v_pk_fma_f32 v[116:117], v[116:117], v[132:133], v[164:165]
	v_pk_fma_f32 v[118:119], v[118:119], v[134:135], v[180:181]
	v_pk_fma_f32 v[104:105], v[104:105], v[128:129], v[210:211]
	v_pk_fma_f32 v[106:107], v[106:107], v[130:131], v[182:183]
	v_cvt_pk_bf16_f32 v116, v116, v117
	v_cvt_pk_bf16_f32 v117, v118, v119
	v_cvt_pk_bf16_f32 v118, v104, v105
	v_cvt_pk_bf16_f32 v119, v106, v107
	global_store_dwordx4 v[162:163], v[116:119], off
	s_waitcnt vmcnt(15)
	v_lshlrev_b32_e32 v164, 16, v184
	v_and_b32_e32 v165, 0xffff0000, v184
	v_lshlrev_b32_e32 v184, 16, v185
	v_and_b32_e32 v185, 0xffff0000, v185
	v_lshlrev_b32_e32 v210, 16, v186
	v_and_b32_e32 v211, 0xffff0000, v186
	v_lshlrev_b32_e32 v186, 16, v187
	v_and_b32_e32 v187, 0xffff0000, v187
	v_pk_fma_f32 v[96:97], v[96:97], v[124:125], v[164:165]
	v_pk_fma_f32 v[98:99], v[98:99], v[126:127], v[184:185]
	v_pk_fma_f32 v[92:93], v[92:93], v[120:121], v[210:211]
	v_pk_fma_f32 v[94:95], v[94:95], v[122:123], v[186:187]
	v_cvt_pk_bf16_f32 v96, v96, v97
	v_cvt_pk_bf16_f32 v97, v98, v99
	v_cvt_pk_bf16_f32 v98, v92, v93
	v_cvt_pk_bf16_f32 v99, v94, v95
	global_store_dwordx4 v[162:163], v[96:99], off offset:256
	s_mov_b64 s[0:1], 0x10000
	v_lshl_add_u64 v[162:163], v[162:163], 0, s[0:1]
	s_waitcnt vmcnt(15)
	v_lshlrev_b32_e32 v164, 16, v190
	v_and_b32_e32 v165, 0xffff0000, v190
	v_lshlrev_b32_e32 v190, 16, v191
	v_and_b32_e32 v191, 0xffff0000, v191
	v_lshlrev_b32_e32 v210, 16, v192
	v_and_b32_e32 v211, 0xffff0000, v192
	v_lshlrev_b32_e32 v192, 16, v193
	v_and_b32_e32 v193, 0xffff0000, v193
	v_pk_fma_f32 v[100:101], v[100:101], v[132:133], v[164:165]
	v_pk_fma_f32 v[102:103], v[102:103], v[134:135], v[190:191]
	v_pk_fma_f32 v[88:89], v[88:89], v[128:129], v[210:211]
	v_pk_fma_f32 v[90:91], v[90:91], v[130:131], v[192:193]
	v_cvt_pk_bf16_f32 v100, v100, v101
	v_cvt_pk_bf16_f32 v101, v102, v103
	v_cvt_pk_bf16_f32 v102, v88, v89
	v_cvt_pk_bf16_f32 v103, v90, v91
	global_store_dwordx4 v[162:163], v[100:103], off
	s_waitcnt vmcnt(15)
; __device__ __forceinline__ unsigned cvt_pk_bf16(float lo, float hi) { unsigned r; asm volatile("v_cvt_pk_bf16_f32 %0, %1, %2" : "=v"(r) : "v"(lo), "v"(hi)); return r; }
; __device__ __forceinline__ float bflo(unsigned w) { return __uint_as_float(w << 16); }
; __device__ __forceinline__ float bfhi(unsigned w) { return __uint_as_float(w & 0xffff0000u); }
;     __device__ __forceinline__ void operator()(const f32x4 (&acc)[2][2][4][2], const Unit& u, int wr, int wc, int fr, int fq) const {
;     ...
;         for (int ai = 0; ai < 2; ++ai)
; #pragma unroll
;             for (int m = 0; m < 4; ++m) { const size_t off = (size_t)(row0 + ai * HALF + m * 16) * 2048 + col0;
; #pragma unroll
;                 for (int bj = 0; bj < 2; ++bj) { f32x4 b0, b1;
;                     if constexpr (sizeof(TB) == 4) { b0 = __builtin_nontemporal_load((const f32x4*)((const float*)base + off + bj * HALF)); b1 = __builtin_nontemporal_load((const f32x4*)((const float*)base + off + bj * HALF + 4)); }
;                     else { const u32x4 t = *(const u32x4*)((const bf16_t*)base + off + bj * HALF);
;                         b0[0] = bflo(t[0]); b0[1] = bfhi(t[0]); b0[2] = bflo(t[1]); b0[3] = bfhi(t[1]); b1[0] = bflo(t[2]); b1[1] = bfhi(t[2]); b1[2] = bflo(t[3]); b1[3] = bfhi(t[3]); }
;                     const f32x4 v0 = b0 + gv[bj][0] * acc[ai][bj][m][0], v1 = b1 + gv[bj][1] * acc[ai][bj][m][1];
;                     u32x4 w; w.x = cvt_pk_bf16(v0[0], v0[1]); w.y = cvt_pk_bf16(v0[2], v0[3]); w.z = cvt_pk_bf16(v1[0], v1[1]); w.w = cvt_pk_bf16(v1[2], v1[3]);
;                     *(u32x4*)(out + off + bj * HALF) = w; } }
	v_lshlrev_b32_e32 v164, 16, v194
	v_and_b32_e32 v165, 0xffff0000, v194
	v_lshlrev_b32_e32 v194, 16, v195
	v_and_b32_e32 v195, 0xffff0000, v195
	v_lshlrev_b32_e32 v210, 16, v196
	v_and_b32_e32 v211, 0xffff0000, v196
	v_lshlrev_b32_e32 v196, 16, v197
	v_and_b32_e32 v197, 0xffff0000, v197
	v_pk_fma_f32 v[80:81], v[80:81], v[124:125], v[164:165]
	v_pk_fma_f32 v[82:83], v[82:83], v[126:127], v[194:195]
	v_pk_fma_f32 v[76:77], v[76:77], v[120:121], v[210:211]
	v_pk_fma_f32 v[78:79], v[78:79], v[122:123], v[196:197]
	v_cvt_pk_bf16_f32 v80, v80, v81
	v_cvt_pk_bf16_f32 v81, v82, v83
	v_cvt_pk_bf16_f32 v82, v76, v77
	v_cvt_pk_bf16_f32 v83, v78, v79
	global_store_dwordx4 v[162:163], v[80:83], off offset:256
	s_mov_b64 s[0:1], 0x10000
	v_lshl_add_u64 v[162:163], v[162:163], 0, s[0:1]
	s_waitcnt vmcnt(15)
	v_lshlrev_b32_e32 v164, 16, v198
	v_and_b32_e32 v165, 0xffff0000, v198
	v_lshlrev_b32_e32 v198, 16, v199
	v_and_b32_e32 v199, 0xffff0000, v199
	v_lshlrev_b32_e32 v210, 16, v200
	v_and_b32_e32 v211, 0xffff0000, v200
	v_lshlrev_b32_e32 v200, 16, v201
	v_and_b32_e32 v201, 0xffff0000, v201
	v_pk_fma_f32 v[84:85], v[84:85], v[132:133], v[164:165]
	v_pk_fma_f32 v[86:87], v[86:87], v[134:135], v[198:199]
	v_pk_fma_f32 v[72:73], v[72:73], v[128:129], v[210:211]
	v_pk_fma_f32 v[74:75], v[74:75], v[130:131], v[200:201]
	v_cvt_pk_bf16_f32 v84, v84, v85
	v_cvt_pk_bf16_f32 v85, v86, v87
	v_cvt_pk_bf16_f32 v86, v72, v73
	v_cvt_pk_bf16_f32 v87, v74, v75
	global_store_dwordx4 v[162:163], v[84:87], off
	s_waitcnt vmcnt(15)
	v_lshlrev_b32_e32 v164, 16, v202
	v_and_b32_e32 v165, 0xffff0000, v202
	v_lshlrev_b32_e32 v202, 16, v203
	v_and_b32_e32 v203, 0xffff0000, v203
	v_lshlrev_b32_e32 v210, 16, v204
	v_and_b32_e32 v211, 0xffff0000, v204
	v_lshlrev_b32_e32 v204, 16, v205
	v_and_b32_e32 v205, 0xffff0000, v205
	v_pk_fma_f32 v[68:69], v[68:69], v[124:125], v[164:165]
	v_pk_fma_f32 v[70:71], v[70:71], v[126:127], v[202:203]
	v_pk_fma_f32 v[64:65], v[64:65], v[120:121], v[210:211]
	v_pk_fma_f32 v[66:67], v[66:67], v[122:123], v[204:205]
	v_cvt_pk_bf16_f32 v68, v68, v69
	v_cvt_pk_bf16_f32 v69, v70, v71
	v_cvt_pk_bf16_f32 v70, v64, v65
	v_cvt_pk_bf16_f32 v71, v66, v67
	global_store_dwordx4 v[162:163], v[68:71], off offset:256
	s_mov_b64 s[0:1], 0x50000
	v_lshl_add_u64 v[162:163], v[162:163], 0, s[0:1]
	s_waitcnt vmcnt(15)
	v_lshlrev_b32_e32 v164, 16, v206
	v_and_b32_e32 v165, 0xffff0000, v206
	v_lshlrev_b32_e32 v206, 16, v207
	v_and_b32_e32 v207, 0xffff0000, v207
	v_lshlrev_b32_e32 v210, 16, v208
	v_and_b32_e32 v211, 0xffff0000, v208
	v_lshlrev_b32_e32 v208, 16, v209
	v_and_b32_e32 v209, 0xffff0000, v209
	v_pk_fma_f32 v[60:61], v[60:61], v[132:133], v[164:165]
	v_pk_fma_f32 v[62:63], v[62:63], v[134:135], v[206:207]
	v_pk_fma_f32 v[56:57], v[56:57], v[128:129], v[210:211]
	v_pk_fma_f32 v[58:59], v[58:59], v[130:131], v[208:209]
	v_cvt_pk_bf16_f32 v60, v60, v61
	v_cvt_pk_bf16_f32 v61, v62, v63
	v_cvt_pk_bf16_f32 v62, v56, v57
	v_cvt_pk_bf16_f32 v63, v58, v59
	global_store_dwordx4 v[162:163], v[60:63], off
	s_waitcnt vmcnt(15)
	v_lshlrev_b32_e32 v164, 16, v214
	v_and_b32_e32 v165, 0xffff0000, v214
	v_lshlrev_b32_e32 v214, 16, v215
	v_and_b32_e32 v215, 0xffff0000, v215
	v_lshlrev_b32_e32 v210, 16, v216
	v_and_b32_e32 v211, 0xffff0000, v216
	v_lshlrev_b32_e32 v216, 16, v217
	v_and_b32_e32 v217, 0xffff0000, v217
	v_pk_fma_f32 v[48:49], v[48:49], v[124:125], v[164:165]
	v_pk_fma_f32 v[50:51], v[50:51], v[126:127], v[214:215]
	v_pk_fma_f32 v[44:45], v[44:45], v[120:121], v[210:211]
	v_pk_fma_f32 v[46:47], v[46:47], v[122:123], v[216:217]
	v_cvt_pk_bf16_f32 v48, v48, v49
	v_cvt_pk_bf16_f32 v49, v50, v51
	v_cvt_pk_bf16_f32 v50, v44, v45
	v_cvt_pk_bf16_f32 v51, v46, v47
	global_store_dwordx4 v[162:163], v[48:51], off offset:256
	s_mov_b64 s[0:1], 0x10000
	v_lshl_add_u64 v[162:163], v[162:163], 0, s[0:1]
	s_waitcnt vmcnt(15)
	v_lshlrev_b32_e32 v164, 16, v218
	v_and_b32_e32 v165, 0xffff0000, v218
	v_lshlrev_b32_e32 v218, 16, v219
	v_and_b32_e32 v219, 0xffff0000, v219
	v_lshlrev_b32_e32 v210, 16, v220
	v_and_b32_e32 v211, 0xffff0000, v220
	v_lshlrev_b32_e32 v220, 16, v221
	v_and_b32_e32 v221, 0xffff0000, v221
	v_pk_fma_f32 v[52:53], v[52:53], v[132:133], v[164:165]
	v_pk_fma_f32 v[54:55], v[54:55], v[134:135], v[218:219]
	v_pk_fma_f32 v[40:41], v[40:41], v[128:129], v[210:211]
	v_pk_fma_f32 v[42:43], v[42:43], v[130:131], v[220:221]
	v_cvt_pk_bf16_f32 v52, v52, v53
	v_cvt_pk_bf16_f32 v53, v54, v55
	v_cvt_pk_bf16_f32 v54, v40, v41
	v_cvt_pk_bf16_f32 v55, v42, v43
	global_store_dwordx4 v[162:163], v[52:55], off
	s_waitcnt vmcnt(15)
; __device__ __forceinline__ unsigned cvt_pk_bf16(float lo, float hi) { unsigned r; asm volatile("v_cvt_pk_bf16_f32 %0, %1, %2" : "=v"(r) : "v"(lo), "v"(hi)); return r; }
; __device__ __forceinline__ float bflo(unsigned w) { return __uint_as_float(w << 16); }
; __device__ __forceinline__ float bfhi(unsigned w) { return __uint_as_float(w & 0xffff0000u); }
;     __device__ __forceinline__ void operator()(const f32x4 (&acc)[2][2][4][2], const Unit& u, int wr, int wc, int fr, int fq) const {
;     ...
;         for (int ai = 0; ai < 2; ++ai)
; #pragma unroll
;             for (int m = 0; m < 4; ++m) { const size_t off = (size_t)(row0 + ai * HALF + m * 16) * 2048 + col0;
; #pragma unroll
;                 for (int bj = 0; bj < 2; ++bj) { f32x4 b0, b1;
;                     if constexpr (sizeof(TB) == 4) { b0 = __builtin_nontemporal_load((const f32x4*)((const float*)base + off + bj * HALF)); b1 = __builtin_nontemporal_load((const f32x4*)((const float*)base + off + bj * HALF + 4)); }
;                     else { const u32x4 t = *(const u32x4*)((const bf16_t*)base + off + bj * HALF);
;                         b0[0] = bflo(t[0]); b0[1] = bfhi(t[0]); b0[2] = bflo(t[1]); b0[3] = bfhi(t[1]); b1[0] = bflo(t[2]); b1[1] = bfhi(t[2]); b1[2] = bflo(t[3]); b1[3] = bfhi(t[3]); }
;                     const f32x4 v0 = b0 + gv[bj][0] * acc[ai][bj][m][0], v1 = b1 + gv[bj][1] * acc[ai][bj][m][1];
;                     u32x4 w; w.x = cvt_pk_bf16(v0[0], v0[1]); w.y = cvt_pk_bf16(v0[2], v0[3]); w.z = cvt_pk_bf16(v1[0], v1[1]); w.w = cvt_pk_bf16(v1[2], v1[3]);
;                     *(u32x4*)(out + off + bj * HALF) = w; } }
;     }
	v_lshlrev_b32_e32 v164, 16, v222
	v_and_b32_e32 v165, 0xffff0000, v222
	v_lshlrev_b32_e32 v222, 16, v223
	v_and_b32_e32 v223, 0xffff0000, v223
	v_lshlrev_b32_e32 v210, 16, v224
	v_and_b32_e32 v211, 0xffff0000, v224
	v_lshlrev_b32_e32 v224, 16, v225
	v_and_b32_e32 v225, 0xffff0000, v225
	v_pk_fma_f32 v[32:33], v[32:33], v[124:125], v[164:165]
	v_pk_fma_f32 v[34:35], v[34:35], v[126:127], v[222:223]
	v_pk_fma_f32 v[28:29], v[28:29], v[120:121], v[210:211]
	v_pk_fma_f32 v[30:31], v[30:31], v[122:123], v[224:225]
	v_cvt_pk_bf16_f32 v32, v32, v33
	v_cvt_pk_bf16_f32 v33, v34, v35
	v_cvt_pk_bf16_f32 v34, v28, v29
	v_cvt_pk_bf16_f32 v35, v30, v31
	global_store_dwordx4 v[162:163], v[32:35], off offset:256
	s_mov_b64 s[0:1], 0x10000
	v_lshl_add_u64 v[162:163], v[162:163], 0, s[0:1]
	s_waitcnt vmcnt(15)
	v_lshlrev_b32_e32 v164, 16, v226
	v_and_b32_e32 v165, 0xffff0000, v226
	v_lshlrev_b32_e32 v226, 16, v227
	v_and_b32_e32 v227, 0xffff0000, v227
	v_lshlrev_b32_e32 v210, 16, v228
	v_and_b32_e32 v211, 0xffff0000, v228
	v_lshlrev_b32_e32 v228, 16, v229
	v_and_b32_e32 v229, 0xffff0000, v229
	v_pk_fma_f32 v[36:37], v[36:37], v[132:133], v[164:165]
	v_pk_fma_f32 v[38:39], v[38:39], v[134:135], v[226:227]
	v_pk_fma_f32 v[24:25], v[24:25], v[128:129], v[210:211]
	v_pk_fma_f32 v[26:27], v[26:27], v[130:131], v[228:229]
	v_cvt_pk_bf16_f32 v36, v36, v37
	v_cvt_pk_bf16_f32 v37, v38, v39
	v_cvt_pk_bf16_f32 v38, v24, v25
	v_cvt_pk_bf16_f32 v39, v26, v27
	global_store_dwordx4 v[162:163], v[36:39], off
	s_waitcnt vmcnt(15)
	v_lshlrev_b32_e32 v164, 16, v230
	v_and_b32_e32 v165, 0xffff0000, v230
	v_lshlrev_b32_e32 v230, 16, v231
	v_and_b32_e32 v231, 0xffff0000, v231
	v_lshlrev_b32_e32 v210, 16, v232
	v_and_b32_e32 v211, 0xffff0000, v232
	v_lshlrev_b32_e32 v232, 16, v233
	v_and_b32_e32 v233, 0xffff0000, v233
	v_pk_fma_f32 v[16:17], v[16:17], v[124:125], v[164:165]
	v_pk_fma_f32 v[18:19], v[18:19], v[126:127], v[230:231]
	v_pk_fma_f32 v[12:13], v[12:13], v[120:121], v[210:211]
	v_pk_fma_f32 v[14:15], v[14:15], v[122:123], v[232:233]
	v_cvt_pk_bf16_f32 v16, v16, v17
	v_cvt_pk_bf16_f32 v17, v18, v19
	v_cvt_pk_bf16_f32 v18, v12, v13
	v_cvt_pk_bf16_f32 v19, v14, v15
	global_store_dwordx4 v[162:163], v[16:19], off offset:256
	s_mov_b64 s[0:1], 0x10000
	v_lshl_add_u64 v[162:163], v[162:163], 0, s[0:1]
	s_waitcnt vmcnt(15)
	v_lshlrev_b32_e32 v164, 16, v234
	v_and_b32_e32 v165, 0xffff0000, v234
	v_lshlrev_b32_e32 v234, 16, v235
	v_and_b32_e32 v235, 0xffff0000, v235
	v_lshlrev_b32_e32 v210, 16, v236
	v_and_b32_e32 v211, 0xffff0000, v236
	v_lshlrev_b32_e32 v236, 16, v237
	v_and_b32_e32 v237, 0xffff0000, v237
	v_pk_fma_f32 v[20:21], v[20:21], v[132:133], v[164:165]
	v_pk_fma_f32 v[22:23], v[22:23], v[134:135], v[234:235]
	v_pk_fma_f32 v[8:9], v[8:9], v[128:129], v[210:211]
	v_pk_fma_f32 v[10:11], v[10:11], v[130:131], v[236:237]
	v_cvt_pk_bf16_f32 v20, v20, v21
	v_cvt_pk_bf16_f32 v21, v22, v23
	v_cvt_pk_bf16_f32 v22, v8, v9
	v_cvt_pk_bf16_f32 v23, v10, v11
	global_store_dwordx4 v[162:163], v[20:23], off
	s_waitcnt vmcnt(15)
	v_lshlrev_b32_e32 v164, 16, v238
	v_and_b32_e32 v165, 0xffff0000, v238
	v_lshlrev_b32_e32 v238, 16, v239
	v_and_b32_e32 v239, 0xffff0000, v239
	v_lshlrev_b32_e32 v210, 16, v240
	v_and_b32_e32 v211, 0xffff0000, v240
	v_lshlrev_b32_e32 v240, 16, v241
	v_and_b32_e32 v241, 0xffff0000, v241
	v_pk_fma_f32 v[4:5], v[4:5], v[124:125], v[164:165]
	v_pk_fma_f32 v[6:7], v[6:7], v[126:127], v[238:239]
	v_pk_fma_f32 v[0:1], v[0:1], v[120:121], v[210:211]
	v_pk_fma_f32 v[2:3], v[2:3], v[122:123], v[240:241]
	v_cvt_pk_bf16_f32 v4, v4, v5
	v_cvt_pk_bf16_f32 v5, v6, v7
	v_cvt_pk_bf16_f32 v6, v0, v1
	v_cvt_pk_bf16_f32 v7, v2, v3
	global_store_dwordx4 v[162:163], v[4:7], off offset:256
	s_and_b64 vcc, exec, s[2:3]
	s_mov_b64 s[0:1], -1
	s_mov_b32 s22, s48
	s_cbranch_vccnz .LBB0_1089
	s_andn2_b64 vcc, exec, s[6:7]
	s_cbranch_vccnz .LBB0_1088
	s_barrier
	s_branch .LBB0_1088
